# attention: overflow guard from tile probability sum instead of per-tile max tree; slow path recomputes scores
# speedup vs baseline: 1.0943x; 1.0102x over previous
; __device__ __forceinline__ int v_st(int k, int c) { const int kk = (k & ~0xC) | ((k & 4) << 1) | ((k & 8) >> 1); return ((kk >> 3) * 4 + (c >> 5)) * 512 + ((kk & 7) * 32 + (c & 31)) * 2; }
; __device__ __forceinline__ int v_rd_base(int lane) { return ((lane & 3) << 3) | (((lane >> 2) & 3) << 6) | (((lane >> 4) & 1) << 5) | (((lane >> 5) & 1) << 8); }
; __device__ void phase_attn(const Params& p, char* lds) {
;     ...
;   const int tid = threadIdx.x, wid = tid >> 6, lane = tid & 63, r32 = lane & 31, hi = lane >> 5;
;   char* V_lds = lds; char* K_lds = lds + AT_KOFF;
;   float* wsl = (float*)(lds + AT_WOFF) + wid * 64; float* li_l = wsl; float* al_l = wsl + 32;
;   const int skey = tid >> 3, sc8 = (tid & 7) * 8;
;   const int pkey = (tid & 255) >> 2, pc8 = (tid & 3) * 8;
;   const int vst = v_st(skey, sc8), kst = skey * AT_KROW + sc8 * 2, pst = pkey * AT_KROW + (64 + pc8) * 2;
;   const int vb0 = (int)(uintptr_t)V_lds + v_rd_base(lane);
;   const int nitems = NB * 16 * 32;
;   const int xcd = blockIdx.x & 7, slot = blockIdx.x >> 3, per = gridDim.x >> 3;
.LBB0_991:
	s_or_b64 exec, exec, s[4:5]
	s_cmpk_gt_u32 s3, 0xfff
	s_waitcnt vmcnt(7)
	v_and_b32_e32 v128, 56, v183
	v_lshlrev_b32_e32 v168, 11, v161
	s_barrier
	v_and_b32_e32 v175, 63, v178
	v_and_b32_e32 v183, 31, v178
	v_lshrrev_b32_e32 v228, 5, v175
	v_readfirstlane_b32 s14, v178
	v_lshrrev_b32_e32 v229, 3, v178
	v_and_b32_e32 v230, 7, v178
	s_lshr_b32 s14, s14, 6
	s_lshr_b32 s15, s14, 2
	s_and_b32 s43, s3, 7
	s_mov_b32 s23, 0x453a4f54
	v_lshlrev_b32_e32 v129, 4, v230
	v_lshl_or_b32 v129, v229, 12, v129
	v_mul_u32_u24_e32 v167, 0xd0, v229
	v_lshl_add_u32 v167, v230, 4, v167
	v_add_u32_e32 v167, 0x10000, v167
	v_lshrrev_b32_e32 v131, 3, v229
	v_lshlrev_b32_e32 v131, 11, v131
	v_lshrrev_b32_e32 v174, 2, v230
	v_lshl_or_b32 v131, v174, 9, v131
	v_and_b32_e32 v174, 7, v229
	v_lshl_or_b32 v131, v174, 6, v131
	v_and_b32_e32 v174, 3, v178
	v_lshl_or_b32 v131, v174, 4, v131
	v_bfe_u32 v229, v178, 2, 6
	v_lshlrev_b32_e32 v130, 4, v174
	v_lshl_or_b32 v130, v229, 6, v130
	v_mul_u32_u24_e32 v169, 0xd0, v229
	v_lshl_add_u32 v169, v174, 4, v169
	v_add_u32_e32 v169, 0x10080, v169
	v_mul_u32_u24_e32 v170, 0xd0, v183
	v_lshl_add_u32 v170, v228, 4, v170
	v_add_u32_e32 v170, 0x10000, v170
	v_and_b32_e32 v171, 3, v175
	v_lshlrev_b32_e32 v171, 3, v171
	v_bfe_u32 v174, v175, 2, 2
	v_lshl_or_b32 v171, v174, 6, v171
	v_bfe_u32 v174, v175, 4, 1
	v_lshl_or_b32 v171, v174, 5, v171
	v_lshl_or_b32 v171, v228, 8, v171
	s_lshl_b32 s16, s14, 5
	v_add_u32_e32 v174, s16, v183
	v_mul_u32_u24_e32 v234, 0xc00, v174
	v_lshl_add_u32 v234, v228, 4, v234
	v_lshlrev_b32_e32 v235, 2, v228
	v_add_u32_e32 v235, s16, v235
	v_lshlrev_b32_e32 v235, 11, v235
	v_lshl_add_u32 v235, v183, 1, v235
	s_lshl_b32 s17, s14, 8
	s_add_i32 s17, s17, 0x1d000
	v_lshl_add_u32 v244, v183, 2, s17
	v_lshl_add_u32 v245, v228, 4, s17
	s_add_u32 s34, s86, 0x3d796000
	s_addc_u32 s35, s87, 0
	s_lshr_b32 s12, s3, 3

; #define SBAR() __builtin_amdgcn_sched_barrier(0)
; #define SLOAD(i, k0) do { sr_[i].vs = *(const bf16x8*)(Kh + (size_t)((k0) + skey) * 2048 + 64 + sc8); \
;     sr_[i].ks = *(const bf16x8*)(Kh + (size_t)((k0) + skey) * 2048 + sc8); \
;     sr_[i].ps = *(const bf16x8*)(Kp + (size_t)((k0) + pkey) * 32 + pc8); } while (0)
; #define SWRITE(bb, i) do { *(bf16x8*)(V_lds + (bb) * AT_SHMV + vst) = sr_[i].vs; \
;     *(bf16x8*)(K_lds + (bb) * AT_SHMK + kst) = sr_[i].ks; \
;     *(bf16x8*)(K_lds + (bb) * AT_SHMK + pst) = sr_[i].ps; } while (0)
; #define SWAIT() asm volatile("s_waitcnt vmcnt(3)" ::: "memory")
; __device__ __forceinline__ void at_partialSM(f32x16& p0, f32x16& p1, float& m_reg, float& alpha, bool force) {
;     ...
;   for (int r = 0; r < 16; ++r) p0[r] = __builtin_amdgcn_exp2f(p0[r]);
; }
; __device__ __forceinline__ void at_finishSM(f32x16& p0, f32x16& p1, float alpha, float& l_reg, bf16x8& pa0, bf16x8& pa1, bf16x8& pa2, bf16x8& pa3) {
; #pragma unroll
;   for (int r = 0; r < 16; ++r) p1[r] = __builtin_amdgcn_exp2f(p1[r]);
;   float ps = 0;
; #pragma unroll
;   for (int r = 0; r < 16; ++r) ps += p0[r];
; #pragma unroll
;   for (int r = 0; r < 16; ++r) ps += p1[r];
;   { auto rr = __builtin_amdgcn_permlane32_swap(__float_as_uint(ps), __float_as_uint(ps), false, false);
;     ps = __uint_as_float(rr[0]) + __uint_as_float(rr[1]); }
;   l_reg = l_reg * alpha + ps;
; __device__ void phase_attn(const Params& p, char* lds) {
;     ...
;     for (int j = 1; j + 1 < NT; j += 2) {
;       SBAR(); at_qkt(pB0, pB1, K_lds + AT_SHMK, qr, r32, hi, -m_reg);
;       at_finishSM(pA0, pA1, alA, l_reg, pa0, pa1, pa2, pa3); SBAR();
;       SLOAD(1, (j + 2) * 64); SBAR();
;       pv_d0(o, vb0, pa0, pa1, pa2, pa3); at_partialSM(pB0, pB1, m_reg, alB, false);
;       __syncthreads(); SWAIT(); SWRITE(0, 0);
;       RESC(alB); __syncthreads();
;       SBAR(); at_qkt(pA0, pA1, K_lds, qr, r32, hi, -m_reg);
;       at_finishSM(pB0, pB1, alB, l_reg, pa0, pa1, pa2, pa3); SBAR();
;       if (j + 3 < NT) SLOAD(0, (j + 3) * 64); SBAR();
;       pv_d0(o, vb0 + AT_SHMV, pa0, pa1, pa2, pa3); at_partialSM(pA0, pA1, m_reg, alA, false);
;       __syncthreads(); SWAIT(); SWRITE(1, 1);
;       RESC(alA); __syncthreads();
;     }
.Lat_loop:
	ds_read_b128 v[200:203], v170 offset:13376
	ds_read_b128 v[204:207], v170 offset:20032
	s_waitcnt lgkmcnt(5)
	v_mfma_f32_32x32x16_bf16 v[32:47], v[184:187], v[80:83], v[64:79]
	s_waitcnt lgkmcnt(4)
	v_mfma_f32_32x32x16_bf16 v[48:63], v[188:191], v[80:83], v[64:79]
	ds_read_b128 v[208:211], v170 offset:13408
	ds_read_b128 v[212:215], v170 offset:20064
	s_waitcnt lgkmcnt(5)
	v_mfma_f32_32x32x16_bf16 v[32:47], v[192:195], v[84:87], v[32:47]
	s_waitcnt lgkmcnt(4)
	v_mfma_f32_32x32x16_bf16 v[48:63], v[196:199], v[84:87], v[48:63]
	ds_read_b128 v[184:187], v170 offset:13440
	ds_read_b128 v[188:191], v170 offset:20096
	s_waitcnt lgkmcnt(5)
	v_mfma_f32_32x32x16_bf16 v[32:47], v[200:203], v[88:91], v[32:47]
	s_waitcnt lgkmcnt(4)
	v_mfma_f32_32x32x16_bf16 v[48:63], v[204:207], v[88:91], v[48:63]
	ds_read_b128 v[192:195], v170 offset:13472
	ds_read_b128 v[196:199], v170 offset:20128
	s_waitcnt lgkmcnt(5)
	v_mfma_f32_32x32x16_bf16 v[32:47], v[208:211], v[92:95], v[32:47]
	s_waitcnt lgkmcnt(4)
	v_mfma_f32_32x32x16_bf16 v[48:63], v[212:215], v[92:95], v[48:63]
	ds_read_b64_tr_b16 v[148:149], v171 offset:0
	ds_read_b64_tr_b16 v[150:151], v171 offset:2048
	ds_read_b64_tr_b16 v[152:153], v171 offset:4096
	ds_read_b64_tr_b16 v[154:155], v171 offset:6144
	s_waitcnt lgkmcnt(7)
	v_mfma_f32_32x32x16_bf16 v[32:47], v[184:187], v[96:99], v[32:47]
	s_waitcnt lgkmcnt(6)
	v_mfma_f32_32x32x16_bf16 v[48:63], v[188:191], v[96:99], v[48:63]
	ds_read_b64_tr_b16 v[156:157], v171 offset:8192
	ds_read_b64_tr_b16 v[158:159], v171 offset:10240
	ds_read_b64_tr_b16 v[216:217], v171 offset:12288
	ds_read_b64_tr_b16 v[218:219], v171 offset:14336
	s_waitcnt lgkmcnt(9)
	v_mfma_f32_32x32x16_bf16 v[32:47], v[192:195], v[100:103], v[32:47]
	s_waitcnt lgkmcnt(8)
	v_mfma_f32_32x32x16_bf16 v[48:63], v[196:199], v[100:103], v[48:63]
	ds_read_b64_tr_b16 v[220:221], v171 offset:512
	ds_read_b64_tr_b16 v[222:223], v171 offset:2560
	ds_read_b64_tr_b16 v[224:225], v171 offset:4608
	ds_read_b64_tr_b16 v[226:227], v171 offset:6656
	s_waitcnt lgkmcnt(10)
	v_mfma_f32_32x32x16_bf16 v[0:15], v[104:107], v[148:151], v[0:15]
	s_waitcnt lgkmcnt(8)
	v_mfma_f32_32x32x16_bf16 v[0:15], v[108:111], v[152:155], v[0:15]
	ds_read_b64_tr_b16 v[236:237], v171 offset:8704
	ds_read_b64_tr_b16 v[238:239], v171 offset:10752
	ds_read_b64_tr_b16 v[240:241], v171 offset:12800
	ds_read_b64_tr_b16 v[242:243], v171 offset:14848
	s_waitcnt lgkmcnt(10)
	v_mfma_f32_32x32x16_bf16 v[0:15], v[112:115], v[156:159], v[0:15]
	s_waitcnt lgkmcnt(8)
	v_mfma_f32_32x32x16_bf16 v[0:15], v[116:119], v[216:219], v[0:15]
	s_waitcnt lgkmcnt(6)
	v_mfma_f32_32x32x16_bf16 v[16:31], v[104:107], v[220:223], v[16:31]
	s_waitcnt lgkmcnt(4)
	v_mfma_f32_32x32x16_bf16 v[16:31], v[108:111], v[224:227], v[16:31]
	s_waitcnt lgkmcnt(2)
	v_mfma_f32_32x32x16_bf16 v[16:31], v[112:115], v[236:239], v[16:31]
	s_waitcnt lgkmcnt(0)
	v_mfma_f32_32x32x16_bf16 v[16:31], v[116:119], v[240:243], v[16:31]
	s_barrier
	s_waitcnt vmcnt(0)
	ds_write_b128 v167, v[120:123] offset:39936
	ds_write_b128 v131, v[124:127] offset:49152
	ds_write_b128 v169, v[132:135] offset:39936
	v_exp_f32_e32 v32, v32
	v_exp_f32_e32 v48, v48
	v_exp_f32_e32 v33, v33
	v_exp_f32_e32 v49, v49
	v_exp_f32_e32 v34, v34
	v_exp_f32_e32 v50, v50
	v_exp_f32_e32 v35, v35
	v_exp_f32_e32 v51, v51
	v_exp_f32_e32 v36, v36
	v_exp_f32_e32 v52, v52
	v_exp_f32_e32 v37, v37
	v_exp_f32_e32 v53, v53
	v_exp_f32_e32 v38, v38
	v_exp_f32_e32 v54, v54
	v_exp_f32_e32 v39, v39
	v_exp_f32_e32 v55, v55
	v_exp_f32_e32 v40, v40
	v_exp_f32_e32 v56, v56
	v_exp_f32_e32 v41, v41
	v_exp_f32_e32 v57, v57
	v_exp_f32_e32 v42, v42
	v_exp_f32_e32 v58, v58
	v_exp_f32_e32 v43, v43
	v_exp_f32_e32 v59, v59
	v_exp_f32_e32 v44, v44
	v_exp_f32_e32 v60, v60
	v_exp_f32_e32 v45, v45
	v_exp_f32_e32 v61, v61
	v_exp_f32_e32 v46, v46
	v_exp_f32_e32 v62, v62
	v_exp_f32_e32 v47, v47
	v_exp_f32_e32 v63, v63
	s_waitcnt lgkmcnt(0)
	global_load_dwordx4 v[120:123], v129, s[4:5]
	global_load_dwordx4 v[124:127], v129, s[4:5] offset:128
	global_load_dwordx4 v[132:135], v130, s[6:7]
	s_add_u32 s4, s4, 0x40000
	s_addc_u32 s5, s5, 0
	s_add_u32 s6, s6, 0x1000
	s_addc_u32 s7, s7, 0
	v_add_f32_e32 v175, v32, v33
	v_add_f32_e32 v174, v48, v49
	v_add_f32_e32 v175, v175, v34
	v_add_f32_e32 v174, v174, v50
	v_add_f32_e32 v175, v175, v35
	v_add_f32_e32 v174, v174, v51
	v_add_f32_e32 v175, v175, v36
	v_add_f32_e32 v174, v174, v52
	v_add_f32_e32 v175, v175, v37
	v_add_f32_e32 v174, v174, v53
	v_add_f32_e32 v175, v175, v38
	v_add_f32_e32 v174, v174, v54
	v_add_f32_e32 v175, v175, v39
	v_add_f32_e32 v174, v174, v55
	v_add_f32_e32 v175, v175, v40
	v_add_f32_e32 v174, v174, v56
	v_add_f32_e32 v175, v175, v41
	v_add_f32_e32 v174, v174, v57
	v_add_f32_e32 v175, v175, v42
	v_add_f32_e32 v174, v174, v58
	v_add_f32_e32 v175, v175, v43
	v_add_f32_e32 v174, v174, v59
	v_add_f32_e32 v175, v175, v44
	v_add_f32_e32 v174, v174, v60
	v_add_f32_e32 v175, v175, v45
	v_add_f32_e32 v174, v174, v61
	v_add_f32_e32 v175, v175, v46
	v_add_f32_e32 v174, v174, v62
	v_add_f32_e32 v175, v175, v47
	v_add_f32_e32 v174, v174, v63
	v_add_f32_e32 v175, v175, v174
	v_cmp_ge_f32_e32 vcc, s23, v175
	s_cmp_eq_u64 vcc, exec
	s_cbranch_scc0 .Lat_rare0
; #define SBAR() __builtin_amdgcn_sched_barrier(0)
; #define SLOAD(i, k0) do { sr_[i].vs = *(const bf16x8*)(Kh + (size_t)((k0) + skey) * 2048 + 64 + sc8); \
;     sr_[i].ks = *(const bf16x8*)(Kh + (size_t)((k0) + skey) * 2048 + sc8); \
;     sr_[i].ps = *(const bf16x8*)(Kp + (size_t)((k0) + pkey) * 32 + pc8); } while (0)
; #define SWRITE(bb, i) do { *(bf16x8*)(V_lds + (bb) * AT_SHMV + vst) = sr_[i].vs; \
;     *(bf16x8*)(K_lds + (bb) * AT_SHMK + kst) = sr_[i].ks; \
;     *(bf16x8*)(K_lds + (bb) * AT_SHMK + pst) = sr_[i].ps; } while (0)
; #define SWAIT() asm volatile("s_waitcnt vmcnt(3)" ::: "memory")
; __device__ __forceinline__ void at_partialSM(f32x16& p0, f32x16& p1, float& m_reg, float& alpha, bool force) {
;     ...
;   for (int r = 0; r < 16; ++r) p0[r] = __builtin_amdgcn_exp2f(p0[r]);
; }
; __device__ __forceinline__ void at_finishSM(f32x16& p0, f32x16& p1, float alpha, float& l_reg, bf16x8& pa0, bf16x8& pa1, bf16x8& pa2, bf16x8& pa3) {
; #pragma unroll
;   for (int r = 0; r < 16; ++r) p1[r] = __builtin_amdgcn_exp2f(p1[r]);
;   float ps = 0;
; #pragma unroll
;   for (int r = 0; r < 16; ++r) ps += p0[r];
; #pragma unroll
;   for (int r = 0; r < 16; ++r) ps += p1[r];
;   { auto rr = __builtin_amdgcn_permlane32_swap(__float_as_uint(ps), __float_as_uint(ps), false, false);
;     ps = __uint_as_float(rr[0]) + __uint_as_float(rr[1]); }
;   l_reg = l_reg * alpha + ps;
; __device__ void phase_attn(const Params& p, char* lds) {
;     ...
;     for (int j = 1; j + 1 < NT; j += 2) {
;       SBAR(); at_qkt(pB0, pB1, K_lds + AT_SHMK, qr, r32, hi, -m_reg);
;       at_finishSM(pA0, pA1, alA, l_reg, pa0, pa1, pa2, pa3); SBAR();
;       SLOAD(1, (j + 2) * 64); SBAR();
;       pv_d0(o, vb0, pa0, pa1, pa2, pa3); at_partialSM(pB0, pB1, m_reg, alB, false);
;       __syncthreads(); SWAIT(); SWRITE(0, 0);
;       RESC(alB); __syncthreads();
;       SBAR(); at_qkt(pA0, pA1, K_lds, qr, r32, hi, -m_reg);
;       at_finishSM(pB0, pB1, alB, l_reg, pa0, pa1, pa2, pa3); SBAR();
;       if (j + 3 < NT) SLOAD(0, (j + 3) * 64); SBAR();
;       pv_d0(o, vb0 + AT_SHMV, pa0, pa1, pa2, pa3); at_partialSM(pA0, pA1, m_reg, alA, false);
;       __syncthreads(); SWAIT(); SWRITE(1, 1);
;       RESC(alA); __syncthreads();
;     }
.Lat_rare0_back:
	v_add_f32_e32 v173, v173, v175
	v_cvt_pk_bf16_f32 v104, v32, v33
	v_cvt_pk_bf16_f32 v105, v34, v35
	v_cvt_pk_bf16_f32 v106, v36, v37
	v_cvt_pk_bf16_f32 v107, v38, v39
	v_cvt_pk_bf16_f32 v108, v40, v41
	v_cvt_pk_bf16_f32 v109, v42, v43
	v_cvt_pk_bf16_f32 v110, v44, v45
	v_cvt_pk_bf16_f32 v111, v46, v47
	v_cvt_pk_bf16_f32 v112, v48, v49
	v_cvt_pk_bf16_f32 v113, v50, v51
	v_cvt_pk_bf16_f32 v114, v52, v53
	v_cvt_pk_bf16_f32 v115, v54, v55
	v_cvt_pk_bf16_f32 v116, v56, v57
	v_cvt_pk_bf16_f32 v117, v58, v59
	v_cvt_pk_bf16_f32 v118, v60, v61
	v_cvt_pk_bf16_f32 v119, v62, v63
	ds_read_b128 v[184:187], v170 offset:26624
	ds_read_b128 v[188:191], v170 offset:33280
	ds_read_b128 v[192:195], v170 offset:26656
	ds_read_b128 v[196:199], v170 offset:33312
	s_barrier
	ds_read_b128 v[200:203], v170 offset:26688
	ds_read_b128 v[204:207], v170 offset:33344
	s_waitcnt lgkmcnt(5)
	v_mfma_f32_32x32x16_bf16 v[32:47], v[184:187], v[80:83], v[64:79]
	s_waitcnt lgkmcnt(4)
	v_mfma_f32_32x32x16_bf16 v[48:63], v[188:191], v[80:83], v[64:79]
	ds_read_b128 v[208:211], v170 offset:26720
	ds_read_b128 v[212:215], v170 offset:33376
	s_waitcnt lgkmcnt(5)
	v_mfma_f32_32x32x16_bf16 v[32:47], v[192:195], v[84:87], v[32:47]
	s_waitcnt lgkmcnt(4)
	v_mfma_f32_32x32x16_bf16 v[48:63], v[196:199], v[84:87], v[48:63]
	ds_read_b128 v[184:187], v170 offset:26752
	ds_read_b128 v[188:191], v170 offset:33408
	s_waitcnt lgkmcnt(5)
	v_mfma_f32_32x32x16_bf16 v[32:47], v[200:203], v[88:91], v[32:47]
	s_waitcnt lgkmcnt(4)
	v_mfma_f32_32x32x16_bf16 v[48:63], v[204:207], v[88:91], v[48:63]
	ds_read_b128 v[192:195], v170 offset:26784
	ds_read_b128 v[196:199], v170 offset:33440
	s_waitcnt lgkmcnt(5)
	v_mfma_f32_32x32x16_bf16 v[32:47], v[208:211], v[92:95], v[32:47]
	s_waitcnt lgkmcnt(4)
	v_mfma_f32_32x32x16_bf16 v[48:63], v[212:215], v[92:95], v[48:63]
	ds_read_b64_tr_b16 v[148:149], v171 offset:16384
	ds_read_b64_tr_b16 v[150:151], v171 offset:18432
	ds_read_b64_tr_b16 v[152:153], v171 offset:20480
	ds_read_b64_tr_b16 v[154:155], v171 offset:22528
	s_waitcnt lgkmcnt(7)
	v_mfma_f32_32x32x16_bf16 v[32:47], v[184:187], v[96:99], v[32:47]
	s_waitcnt lgkmcnt(6)
	v_mfma_f32_32x32x16_bf16 v[48:63], v[188:191], v[96:99], v[48:63]
	ds_read_b64_tr_b16 v[156:157], v171 offset:24576
	ds_read_b64_tr_b16 v[158:159], v171 offset:26624
	ds_read_b64_tr_b16 v[216:217], v171 offset:28672
	ds_read_b64_tr_b16 v[218:219], v171 offset:30720
	s_waitcnt lgkmcnt(9)
	v_mfma_f32_32x32x16_bf16 v[32:47], v[192:195], v[100:103], v[32:47]
	s_waitcnt lgkmcnt(8)
	v_mfma_f32_32x32x16_bf16 v[48:63], v[196:199], v[100:103], v[48:63]
	ds_read_b64_tr_b16 v[220:221], v171 offset:16896
	ds_read_b64_tr_b16 v[222:223], v171 offset:18944
	ds_read_b64_tr_b16 v[224:225], v171 offset:20992
	ds_read_b64_tr_b16 v[226:227], v171 offset:23040
	s_waitcnt lgkmcnt(10)
	v_mfma_f32_32x32x16_bf16 v[0:15], v[104:107], v[148:151], v[0:15]
	s_waitcnt lgkmcnt(8)
	v_mfma_f32_32x32x16_bf16 v[0:15], v[108:111], v[152:155], v[0:15]
	ds_read_b64_tr_b16 v[236:237], v171 offset:25088
	ds_read_b64_tr_b16 v[238:239], v171 offset:27136
	ds_read_b64_tr_b16 v[240:241], v171 offset:29184
	ds_read_b64_tr_b16 v[242:243], v171 offset:31232
	s_waitcnt lgkmcnt(10)
	v_mfma_f32_32x32x16_bf16 v[0:15], v[112:115], v[156:159], v[0:15]
	s_waitcnt lgkmcnt(8)
	v_mfma_f32_32x32x16_bf16 v[0:15], v[116:119], v[216:219], v[0:15]
	s_waitcnt lgkmcnt(6)
	v_mfma_f32_32x32x16_bf16 v[16:31], v[104:107], v[220:223], v[16:31]
	s_waitcnt lgkmcnt(4)
	v_mfma_f32_32x32x16_bf16 v[16:31], v[108:111], v[224:227], v[16:31]
	s_waitcnt lgkmcnt(2)
	v_mfma_f32_32x32x16_bf16 v[16:31], v[112:115], v[236:239], v[16:31]
	s_waitcnt lgkmcnt(0)
	v_mfma_f32_32x32x16_bf16 v[16:31], v[116:119], v[240:243], v[16:31]
	s_barrier
	s_waitcnt vmcnt(0)
	ds_write_b128 v167, v[120:123] offset:0
	ds_write_b128 v131, v[124:127] offset:0
	ds_write_b128 v169, v[132:135] offset:0
	v_exp_f32_e32 v32, v32
	v_exp_f32_e32 v48, v48
	v_exp_f32_e32 v33, v33
	v_exp_f32_e32 v49, v49
	v_exp_f32_e32 v34, v34
	v_exp_f32_e32 v50, v50
	v_exp_f32_e32 v35, v35
	v_exp_f32_e32 v51, v51
	v_exp_f32_e32 v36, v36
	v_exp_f32_e32 v52, v52
	v_exp_f32_e32 v37, v37
	v_exp_f32_e32 v53, v53
	v_exp_f32_e32 v38, v38
	v_exp_f32_e32 v54, v54
	v_exp_f32_e32 v39, v39
	v_exp_f32_e32 v55, v55
	v_exp_f32_e32 v40, v40
	v_exp_f32_e32 v56, v56
	v_exp_f32_e32 v41, v41
	v_exp_f32_e32 v57, v57
	v_exp_f32_e32 v42, v42
	v_exp_f32_e32 v58, v58
	v_exp_f32_e32 v43, v43
	v_exp_f32_e32 v59, v59
	v_exp_f32_e32 v44, v44
	v_exp_f32_e32 v60, v60
	v_exp_f32_e32 v45, v45
	v_exp_f32_e32 v61, v61
	v_exp_f32_e32 v46, v46
	v_exp_f32_e32 v62, v62
	v_exp_f32_e32 v47, v47
	v_exp_f32_e32 v63, v63
	s_waitcnt lgkmcnt(0)
	global_load_dwordx4 v[120:123], v129, s[4:5]
	global_load_dwordx4 v[124:127], v129, s[4:5] offset:128
	global_load_dwordx4 v[132:135], v130, s[6:7]
	s_add_u32 s4, s4, 0x40000
	s_addc_u32 s5, s5, 0
	s_add_u32 s6, s6, 0x1000
	s_addc_u32 s7, s7, 0
	v_add_f32_e32 v175, v32, v33
	v_add_f32_e32 v174, v48, v49
	v_add_f32_e32 v175, v175, v34
	v_add_f32_e32 v174, v174, v50
	v_add_f32_e32 v175, v175, v35
	v_add_f32_e32 v174, v174, v51
	v_add_f32_e32 v175, v175, v36
	v_add_f32_e32 v174, v174, v52
	v_add_f32_e32 v175, v175, v37
	v_add_f32_e32 v174, v174, v53
	v_add_f32_e32 v175, v175, v38
	v_add_f32_e32 v174, v174, v54
	v_add_f32_e32 v175, v175, v39
	v_add_f32_e32 v174, v174, v55
	v_add_f32_e32 v175, v175, v40
	v_add_f32_e32 v174, v174, v56
	v_add_f32_e32 v175, v175, v41
	v_add_f32_e32 v174, v174, v57
	v_add_f32_e32 v175, v175, v42
	v_add_f32_e32 v174, v174, v58
	v_add_f32_e32 v175, v175, v43
	v_add_f32_e32 v174, v174, v59
	v_add_f32_e32 v175, v175, v44
	v_add_f32_e32 v174, v174, v60
	v_add_f32_e32 v175, v175, v45
	v_add_f32_e32 v174, v174, v61
	v_add_f32_e32 v175, v175, v46
	v_add_f32_e32 v174, v174, v62
	v_add_f32_e32 v175, v175, v47
	v_add_f32_e32 v174, v174, v63
	v_add_f32_e32 v175, v175, v174
	v_cmp_ge_f32_e32 vcc, s23, v175
	s_cmp_eq_u64 vcc, exec
	s_cbranch_scc0 .Lat_rare1
; #define SBAR() __builtin_amdgcn_sched_barrier(0)
; #define SLOAD(i, k0) do { sr_[i].vs = *(const bf16x8*)(Kh + (size_t)((k0) + skey) * 2048 + 64 + sc8); \
;     sr_[i].ks = *(const bf16x8*)(Kh + (size_t)((k0) + skey) * 2048 + sc8); \
;     sr_[i].ps = *(const bf16x8*)(Kp + (size_t)((k0) + pkey) * 32 + pc8); } while (0)
; #define SWRITE(bb, i) do { *(bf16x8*)(V_lds + (bb) * AT_SHMV + vst) = sr_[i].vs; \
;     *(bf16x8*)(K_lds + (bb) * AT_SHMK + kst) = sr_[i].ks; \
;     *(bf16x8*)(K_lds + (bb) * AT_SHMK + pst) = sr_[i].ps; } while (0)
; #define SWAIT() asm volatile("s_waitcnt vmcnt(3)" ::: "memory")
; __device__ __forceinline__ void at_partialSM(f32x16& p0, f32x16& p1, float& m_reg, float& alpha, bool force) {
;     ...
;   for (int r = 0; r < 16; ++r) p0[r] = __builtin_amdgcn_exp2f(p0[r]);
; }
; __device__ __forceinline__ void at_finishSM(f32x16& p0, f32x16& p1, float alpha, float& l_reg, bf16x8& pa0, bf16x8& pa1, bf16x8& pa2, bf16x8& pa3) {
; #pragma unroll
;   for (int r = 0; r < 16; ++r) p1[r] = __builtin_amdgcn_exp2f(p1[r]);
;   float ps = 0;
; #pragma unroll
;   for (int r = 0; r < 16; ++r) ps += p0[r];
; #pragma unroll
;   for (int r = 0; r < 16; ++r) ps += p1[r];
;   { auto rr = __builtin_amdgcn_permlane32_swap(__float_as_uint(ps), __float_as_uint(ps), false, false);
;     ps = __uint_as_float(rr[0]) + __uint_as_float(rr[1]); }
;   l_reg = l_reg * alpha + ps;
; __device__ void phase_attn(const Params& p, char* lds) {
;     ...
;     for (int j = 1; j + 1 < NT; j += 2) {
;       SBAR(); at_qkt(pB0, pB1, K_lds + AT_SHMK, qr, r32, hi, -m_reg);
;       at_finishSM(pA0, pA1, alA, l_reg, pa0, pa1, pa2, pa3); SBAR();
;       SLOAD(1, (j + 2) * 64); SBAR();
;       pv_d0(o, vb0, pa0, pa1, pa2, pa3); at_partialSM(pB0, pB1, m_reg, alB, false);
;       __syncthreads(); SWAIT(); SWRITE(0, 0);
;       RESC(alB); __syncthreads();
;       SBAR(); at_qkt(pA0, pA1, K_lds, qr, r32, hi, -m_reg);
;       at_finishSM(pB0, pB1, alB, l_reg, pa0, pa1, pa2, pa3); SBAR();
;       if (j + 3 < NT) SLOAD(0, (j + 3) * 64); SBAR();
;       pv_d0(o, vb0 + AT_SHMV, pa0, pa1, pa2, pa3); at_partialSM(pA0, pA1, m_reg, alA, false);
;       __syncthreads(); SWAIT(); SWRITE(1, 1);
;       RESC(alA); __syncthreads();
;     }
.Lat_rare1_back:
	v_add_f32_e32 v173, v173, v175
	v_cvt_pk_bf16_f32 v104, v32, v33
	v_cvt_pk_bf16_f32 v105, v34, v35
	v_cvt_pk_bf16_f32 v106, v36, v37
	v_cvt_pk_bf16_f32 v107, v38, v39
	v_cvt_pk_bf16_f32 v108, v40, v41
	v_cvt_pk_bf16_f32 v109, v42, v43
	v_cvt_pk_bf16_f32 v110, v44, v45
	v_cvt_pk_bf16_f32 v111, v46, v47
	v_cvt_pk_bf16_f32 v112, v48, v49
	v_cvt_pk_bf16_f32 v113, v50, v51
	v_cvt_pk_bf16_f32 v114, v52, v53
	v_cvt_pk_bf16_f32 v115, v54, v55
	v_cvt_pk_bf16_f32 v116, v56, v57
	v_cvt_pk_bf16_f32 v117, v58, v59
	v_cvt_pk_bf16_f32 v118, v60, v61
	v_cvt_pk_bf16_f32 v119, v62, v63
	ds_read_b128 v[184:187], v170 offset:39936
	ds_read_b128 v[188:191], v170 offset:46592
	ds_read_b128 v[192:195], v170 offset:39968
	ds_read_b128 v[196:199], v170 offset:46624
	s_barrier
	ds_read_b128 v[200:203], v170 offset:40000
	ds_read_b128 v[204:207], v170 offset:46656
	s_waitcnt lgkmcnt(5)
	v_mfma_f32_32x32x16_bf16 v[32:47], v[184:187], v[80:83], v[64:79]
	s_waitcnt lgkmcnt(4)
	v_mfma_f32_32x32x16_bf16 v[48:63], v[188:191], v[80:83], v[64:79]
	ds_read_b128 v[208:211], v170 offset:40032
	ds_read_b128 v[212:215], v170 offset:46688
	s_waitcnt lgkmcnt(5)
	v_mfma_f32_32x32x16_bf16 v[32:47], v[192:195], v[84:87], v[32:47]
	s_waitcnt lgkmcnt(4)
	v_mfma_f32_32x32x16_bf16 v[48:63], v[196:199], v[84:87], v[48:63]
	ds_read_b128 v[184:187], v170 offset:40064
	ds_read_b128 v[188:191], v170 offset:46720
	s_waitcnt lgkmcnt(5)
	v_mfma_f32_32x32x16_bf16 v[32:47], v[200:203], v[88:91], v[32:47]
	s_waitcnt lgkmcnt(4)
	v_mfma_f32_32x32x16_bf16 v[48:63], v[204:207], v[88:91], v[48:63]
	ds_read_b128 v[192:195], v170 offset:40096
	ds_read_b128 v[196:199], v170 offset:46752
	s_waitcnt lgkmcnt(5)
	v_mfma_f32_32x32x16_bf16 v[32:47], v[208:211], v[92:95], v[32:47]
	s_waitcnt lgkmcnt(4)
	v_mfma_f32_32x32x16_bf16 v[48:63], v[212:215], v[92:95], v[48:63]
	ds_read_b64_tr_b16 v[148:149], v171 offset:32768
	ds_read_b64_tr_b16 v[150:151], v171 offset:34816
	ds_read_b64_tr_b16 v[152:153], v171 offset:36864
	ds_read_b64_tr_b16 v[154:155], v171 offset:38912
	s_waitcnt lgkmcnt(7)
	v_mfma_f32_32x32x16_bf16 v[32:47], v[184:187], v[96:99], v[32:47]
	s_waitcnt lgkmcnt(6)
	v_mfma_f32_32x32x16_bf16 v[48:63], v[188:191], v[96:99], v[48:63]
	ds_read_b64_tr_b16 v[156:157], v171 offset:40960
	ds_read_b64_tr_b16 v[158:159], v171 offset:43008
	ds_read_b64_tr_b16 v[216:217], v171 offset:45056
	ds_read_b64_tr_b16 v[218:219], v171 offset:47104
	s_waitcnt lgkmcnt(9)
	v_mfma_f32_32x32x16_bf16 v[32:47], v[192:195], v[100:103], v[32:47]
	s_waitcnt lgkmcnt(8)
	v_mfma_f32_32x32x16_bf16 v[48:63], v[196:199], v[100:103], v[48:63]
	ds_read_b64_tr_b16 v[220:221], v171 offset:33280
	ds_read_b64_tr_b16 v[222:223], v171 offset:35328
	ds_read_b64_tr_b16 v[224:225], v171 offset:37376
	ds_read_b64_tr_b16 v[226:227], v171 offset:39424
	s_waitcnt lgkmcnt(10)
	v_mfma_f32_32x32x16_bf16 v[0:15], v[104:107], v[148:151], v[0:15]
	s_waitcnt lgkmcnt(8)
	v_mfma_f32_32x32x16_bf16 v[0:15], v[108:111], v[152:155], v[0:15]
	ds_read_b64_tr_b16 v[236:237], v171 offset:41472
	ds_read_b64_tr_b16 v[238:239], v171 offset:43520
	ds_read_b64_tr_b16 v[240:241], v171 offset:45568
	ds_read_b64_tr_b16 v[242:243], v171 offset:47616
	s_waitcnt lgkmcnt(10)
	v_mfma_f32_32x32x16_bf16 v[0:15], v[112:115], v[156:159], v[0:15]
	s_waitcnt lgkmcnt(8)
	v_mfma_f32_32x32x16_bf16 v[0:15], v[116:119], v[216:219], v[0:15]
	s_waitcnt lgkmcnt(6)
	v_mfma_f32_32x32x16_bf16 v[16:31], v[104:107], v[220:223], v[16:31]
	s_waitcnt lgkmcnt(4)
	v_mfma_f32_32x32x16_bf16 v[16:31], v[108:111], v[224:227], v[16:31]
	s_waitcnt lgkmcnt(2)
	v_mfma_f32_32x32x16_bf16 v[16:31], v[112:115], v[236:239], v[16:31]
	s_waitcnt lgkmcnt(0)
	v_mfma_f32_32x32x16_bf16 v[16:31], v[116:119], v[240:243], v[16:31]
	s_barrier
	s_waitcnt vmcnt(0)
	ds_write_b128 v167, v[120:123] offset:13312
	ds_write_b128 v131, v[124:127] offset:16384
	ds_write_b128 v169, v[132:135] offset:13312
	v_exp_f32_e32 v32, v32
	v_exp_f32_e32 v48, v48
	v_exp_f32_e32 v33, v33
	v_exp_f32_e32 v49, v49
	v_exp_f32_e32 v34, v34
	v_exp_f32_e32 v50, v50
	v_exp_f32_e32 v35, v35
	v_exp_f32_e32 v51, v51
	v_exp_f32_e32 v36, v36
	v_exp_f32_e32 v52, v52
	v_exp_f32_e32 v37, v37
	v_exp_f32_e32 v53, v53
	v_exp_f32_e32 v38, v38
	v_exp_f32_e32 v54, v54
	v_exp_f32_e32 v39, v39
	v_exp_f32_e32 v55, v55
	v_exp_f32_e32 v40, v40
	v_exp_f32_e32 v56, v56
	v_exp_f32_e32 v41, v41
	v_exp_f32_e32 v57, v57
	v_exp_f32_e32 v42, v42
	v_exp_f32_e32 v58, v58
	v_exp_f32_e32 v43, v43
	v_exp_f32_e32 v59, v59
	v_exp_f32_e32 v44, v44
	v_exp_f32_e32 v60, v60
	v_exp_f32_e32 v45, v45
	v_exp_f32_e32 v61, v61
	v_exp_f32_e32 v46, v46
	v_exp_f32_e32 v62, v62
	v_exp_f32_e32 v47, v47
	v_exp_f32_e32 v63, v63
	s_waitcnt lgkmcnt(0)
	global_load_dwordx4 v[120:123], v129, s[4:5]
	global_load_dwordx4 v[124:127], v129, s[4:5] offset:128
	global_load_dwordx4 v[132:135], v130, s[6:7]
	s_add_u32 s4, s4, 0x40000
	s_addc_u32 s5, s5, 0
	s_add_u32 s6, s6, 0x1000
	s_addc_u32 s7, s7, 0
	v_add_f32_e32 v175, v32, v33
	v_add_f32_e32 v174, v48, v49
	v_add_f32_e32 v175, v175, v34
	v_add_f32_e32 v174, v174, v50
	v_add_f32_e32 v175, v175, v35
	v_add_f32_e32 v174, v174, v51
	v_add_f32_e32 v175, v175, v36
	v_add_f32_e32 v174, v174, v52
	v_add_f32_e32 v175, v175, v37
	v_add_f32_e32 v174, v174, v53
	v_add_f32_e32 v175, v175, v38
	v_add_f32_e32 v174, v174, v54
	v_add_f32_e32 v175, v175, v39
	v_add_f32_e32 v174, v174, v55
	v_add_f32_e32 v175, v175, v40
	v_add_f32_e32 v174, v174, v56
	v_add_f32_e32 v175, v175, v41
	v_add_f32_e32 v174, v174, v57
	v_add_f32_e32 v175, v175, v42
	v_add_f32_e32 v174, v174, v58
	v_add_f32_e32 v175, v175, v43
	v_add_f32_e32 v174, v174, v59
	v_add_f32_e32 v175, v175, v44
	v_add_f32_e32 v174, v174, v60
	v_add_f32_e32 v175, v175, v45
	v_add_f32_e32 v174, v174, v61
	v_add_f32_e32 v175, v175, v46
	v_add_f32_e32 v174, v174, v62
	v_add_f32_e32 v175, v175, v47
	v_add_f32_e32 v174, v174, v63
	v_add_f32_e32 v175, v175, v174
	v_cmp_ge_f32_e32 vcc, s23, v175
	s_cmp_eq_u64 vcc, exec
	s_cbranch_scc0 .Lat_rare2
; #define SBAR() __builtin_amdgcn_sched_barrier(0)
; #define SLOAD(i, k0) do { sr_[i].vs = *(const bf16x8*)(Kh + (size_t)((k0) + skey) * 2048 + 64 + sc8); \
;     sr_[i].ks = *(const bf16x8*)(Kh + (size_t)((k0) + skey) * 2048 + sc8); \
;     sr_[i].ps = *(const bf16x8*)(Kp + (size_t)((k0) + pkey) * 32 + pc8); } while (0)
; #define SWRITE(bb, i) do { *(bf16x8*)(V_lds + (bb) * AT_SHMV + vst) = sr_[i].vs; \
;     *(bf16x8*)(K_lds + (bb) * AT_SHMK + kst) = sr_[i].ks; \
;     *(bf16x8*)(K_lds + (bb) * AT_SHMK + pst) = sr_[i].ps; } while (0)
; #define SWAIT() asm volatile("s_waitcnt vmcnt(3)" ::: "memory")
; __device__ __forceinline__ void at_partialSM(f32x16& p0, f32x16& p1, float& m_reg, float& alpha, bool force) {
;     ...
;   for (int r = 0; r < 16; ++r) p0[r] = __builtin_amdgcn_exp2f(p0[r]);
; }
; __device__ __forceinline__ void at_finishSM(f32x16& p0, f32x16& p1, float alpha, float& l_reg, bf16x8& pa0, bf16x8& pa1, bf16x8& pa2, bf16x8& pa3) {
; #pragma unroll
;   for (int r = 0; r < 16; ++r) p1[r] = __builtin_amdgcn_exp2f(p1[r]);
;   float ps = 0;
; #pragma unroll
;   for (int r = 0; r < 16; ++r) ps += p0[r];
; #pragma unroll
;   for (int r = 0; r < 16; ++r) ps += p1[r];
;   { auto rr = __builtin_amdgcn_permlane32_swap(__float_as_uint(ps), __float_as_uint(ps), false, false);
;     ps = __uint_as_float(rr[0]) + __uint_as_float(rr[1]); }
;   l_reg = l_reg * alpha + ps;
; __device__ void phase_attn(const Params& p, char* lds) {
;     ...
;     for (int j = 1; j + 1 < NT; j += 2) {
;       SBAR(); at_qkt(pB0, pB1, K_lds + AT_SHMK, qr, r32, hi, -m_reg);
;       at_finishSM(pA0, pA1, alA, l_reg, pa0, pa1, pa2, pa3); SBAR();
;       SLOAD(1, (j + 2) * 64); SBAR();
;       pv_d0(o, vb0, pa0, pa1, pa2, pa3); at_partialSM(pB0, pB1, m_reg, alB, false);
;       __syncthreads(); SWAIT(); SWRITE(0, 0);
;       RESC(alB); __syncthreads();
;       SBAR(); at_qkt(pA0, pA1, K_lds, qr, r32, hi, -m_reg);
;       at_finishSM(pB0, pB1, alB, l_reg, pa0, pa1, pa2, pa3); SBAR();
;       if (j + 3 < NT) SLOAD(0, (j + 3) * 64); SBAR();
;       pv_d0(o, vb0 + AT_SHMV, pa0, pa1, pa2, pa3); at_partialSM(pA0, pA1, m_reg, alA, false);
;       __syncthreads(); SWAIT(); SWRITE(1, 1);
;       RESC(alA); __syncthreads();
;     }
.Lat_rare2_back:
	v_add_f32_e32 v173, v173, v175
	v_cvt_pk_bf16_f32 v104, v32, v33
	v_cvt_pk_bf16_f32 v105, v34, v35
	v_cvt_pk_bf16_f32 v106, v36, v37
	v_cvt_pk_bf16_f32 v107, v38, v39
	v_cvt_pk_bf16_f32 v108, v40, v41
	v_cvt_pk_bf16_f32 v109, v42, v43
	v_cvt_pk_bf16_f32 v110, v44, v45
	v_cvt_pk_bf16_f32 v111, v46, v47
	v_cvt_pk_bf16_f32 v112, v48, v49
	v_cvt_pk_bf16_f32 v113, v50, v51
	v_cvt_pk_bf16_f32 v114, v52, v53
	v_cvt_pk_bf16_f32 v115, v54, v55
	v_cvt_pk_bf16_f32 v116, v56, v57
	v_cvt_pk_bf16_f32 v117, v58, v59
	v_cvt_pk_bf16_f32 v118, v60, v61
	v_cvt_pk_bf16_f32 v119, v62, v63
	ds_read_b128 v[184:187], v170 offset:0
	ds_read_b128 v[188:191], v170 offset:6656
	ds_read_b128 v[192:195], v170 offset:32
	ds_read_b128 v[196:199], v170 offset:6688
	s_barrier
	ds_read_b128 v[200:203], v170 offset:64
	ds_read_b128 v[204:207], v170 offset:6720
	s_waitcnt lgkmcnt(5)
	v_mfma_f32_32x32x16_bf16 v[32:47], v[184:187], v[80:83], v[64:79]
	s_waitcnt lgkmcnt(4)
	v_mfma_f32_32x32x16_bf16 v[48:63], v[188:191], v[80:83], v[64:79]
	ds_read_b128 v[208:211], v170 offset:96
	ds_read_b128 v[212:215], v170 offset:6752
	s_waitcnt lgkmcnt(5)
	v_mfma_f32_32x32x16_bf16 v[32:47], v[192:195], v[84:87], v[32:47]
	s_waitcnt lgkmcnt(4)
	v_mfma_f32_32x32x16_bf16 v[48:63], v[196:199], v[84:87], v[48:63]
	ds_read_b128 v[184:187], v170 offset:128
	ds_read_b128 v[188:191], v170 offset:6784
	s_waitcnt lgkmcnt(5)
	v_mfma_f32_32x32x16_bf16 v[32:47], v[200:203], v[88:91], v[32:47]
	s_waitcnt lgkmcnt(4)
	v_mfma_f32_32x32x16_bf16 v[48:63], v[204:207], v[88:91], v[48:63]
	ds_read_b128 v[192:195], v170 offset:160
	ds_read_b128 v[196:199], v170 offset:6816
	s_waitcnt lgkmcnt(5)
	v_mfma_f32_32x32x16_bf16 v[32:47], v[208:211], v[92:95], v[32:47]
	s_waitcnt lgkmcnt(4)
	v_mfma_f32_32x32x16_bf16 v[48:63], v[212:215], v[92:95], v[48:63]
	ds_read_b64_tr_b16 v[148:149], v171 offset:49152
	ds_read_b64_tr_b16 v[150:151], v171 offset:51200
	ds_read_b64_tr_b16 v[152:153], v171 offset:53248
	ds_read_b64_tr_b16 v[154:155], v171 offset:55296
	s_waitcnt lgkmcnt(7)
	v_mfma_f32_32x32x16_bf16 v[32:47], v[184:187], v[96:99], v[32:47]
	s_waitcnt lgkmcnt(6)
	v_mfma_f32_32x32x16_bf16 v[48:63], v[188:191], v[96:99], v[48:63]
	ds_read_b64_tr_b16 v[156:157], v171 offset:57344
	ds_read_b64_tr_b16 v[158:159], v171 offset:59392
	ds_read_b64_tr_b16 v[216:217], v171 offset:61440
	ds_read_b64_tr_b16 v[218:219], v171 offset:63488
	s_waitcnt lgkmcnt(9)
	v_mfma_f32_32x32x16_bf16 v[32:47], v[192:195], v[100:103], v[32:47]
	s_waitcnt lgkmcnt(8)
	v_mfma_f32_32x32x16_bf16 v[48:63], v[196:199], v[100:103], v[48:63]
	ds_read_b64_tr_b16 v[220:221], v171 offset:49664
	ds_read_b64_tr_b16 v[222:223], v171 offset:51712
	ds_read_b64_tr_b16 v[224:225], v171 offset:53760
	ds_read_b64_tr_b16 v[226:227], v171 offset:55808
	s_waitcnt lgkmcnt(10)
	v_mfma_f32_32x32x16_bf16 v[0:15], v[104:107], v[148:151], v[0:15]
	s_waitcnt lgkmcnt(8)
	v_mfma_f32_32x32x16_bf16 v[0:15], v[108:111], v[152:155], v[0:15]
	ds_read_b64_tr_b16 v[236:237], v171 offset:57856
	ds_read_b64_tr_b16 v[238:239], v171 offset:59904
	ds_read_b64_tr_b16 v[240:241], v171 offset:61952
	ds_read_b64_tr_b16 v[242:243], v171 offset:64000
	s_waitcnt lgkmcnt(10)
	v_mfma_f32_32x32x16_bf16 v[0:15], v[112:115], v[156:159], v[0:15]
	s_waitcnt lgkmcnt(8)
	v_mfma_f32_32x32x16_bf16 v[0:15], v[116:119], v[216:219], v[0:15]
	s_waitcnt lgkmcnt(6)
	v_mfma_f32_32x32x16_bf16 v[16:31], v[104:107], v[220:223], v[16:31]
	s_waitcnt lgkmcnt(4)
	v_mfma_f32_32x32x16_bf16 v[16:31], v[108:111], v[224:227], v[16:31]
	s_waitcnt lgkmcnt(2)
	v_mfma_f32_32x32x16_bf16 v[16:31], v[112:115], v[236:239], v[16:31]
	s_waitcnt lgkmcnt(0)
	v_mfma_f32_32x32x16_bf16 v[16:31], v[116:119], v[240:243], v[16:31]
	s_barrier
	s_waitcnt vmcnt(0)
	ds_write_b128 v167, v[120:123] offset:26624
	ds_write_b128 v131, v[124:127] offset:32768
	ds_write_b128 v169, v[132:135] offset:26624
	v_exp_f32_e32 v32, v32
	v_exp_f32_e32 v48, v48
	v_exp_f32_e32 v33, v33
	v_exp_f32_e32 v49, v49
	v_exp_f32_e32 v34, v34
	v_exp_f32_e32 v50, v50
	v_exp_f32_e32 v35, v35
	v_exp_f32_e32 v51, v51
	v_exp_f32_e32 v36, v36
	v_exp_f32_e32 v52, v52
	v_exp_f32_e32 v37, v37
	v_exp_f32_e32 v53, v53
	v_exp_f32_e32 v38, v38
	v_exp_f32_e32 v54, v54
	v_exp_f32_e32 v39, v39
	v_exp_f32_e32 v55, v55
	v_exp_f32_e32 v40, v40
	v_exp_f32_e32 v56, v56
	v_exp_f32_e32 v41, v41
	v_exp_f32_e32 v57, v57
	v_exp_f32_e32 v42, v42
	v_exp_f32_e32 v58, v58
	v_exp_f32_e32 v43, v43
	v_exp_f32_e32 v59, v59
	v_exp_f32_e32 v44, v44
	v_exp_f32_e32 v60, v60
	v_exp_f32_e32 v45, v45
	v_exp_f32_e32 v61, v61
	v_exp_f32_e32 v46, v46
	v_exp_f32_e32 v62, v62
	v_exp_f32_e32 v47, v47
	v_exp_f32_e32 v63, v63
	s_waitcnt lgkmcnt(0)
	global_load_dwordx4 v[120:123], v129, s[4:5]
	global_load_dwordx4 v[124:127], v129, s[4:5] offset:128
	global_load_dwordx4 v[132:135], v130, s[6:7]
	s_add_u32 s4, s4, 0x40000
	s_addc_u32 s5, s5, 0
	s_add_u32 s6, s6, 0x1000
	s_addc_u32 s7, s7, 0
	v_add_f32_e32 v175, v32, v33
	v_add_f32_e32 v174, v48, v49
	v_add_f32_e32 v175, v175, v34
	v_add_f32_e32 v174, v174, v50
	v_add_f32_e32 v175, v175, v35
	v_add_f32_e32 v174, v174, v51
	v_add_f32_e32 v175, v175, v36
	v_add_f32_e32 v174, v174, v52
	v_add_f32_e32 v175, v175, v37
	v_add_f32_e32 v174, v174, v53
	v_add_f32_e32 v175, v175, v38
	v_add_f32_e32 v174, v174, v54
	v_add_f32_e32 v175, v175, v39
	v_add_f32_e32 v174, v174, v55
	v_add_f32_e32 v175, v175, v40
	v_add_f32_e32 v174, v174, v56
	v_add_f32_e32 v175, v175, v41
	v_add_f32_e32 v174, v174, v57
	v_add_f32_e32 v175, v175, v42
	v_add_f32_e32 v174, v174, v58
	v_add_f32_e32 v175, v175, v43
	v_add_f32_e32 v174, v174, v59
	v_add_f32_e32 v175, v175, v44
	v_add_f32_e32 v174, v174, v60
	v_add_f32_e32 v175, v175, v45
	v_add_f32_e32 v174, v174, v61
	v_add_f32_e32 v175, v175, v46
	v_add_f32_e32 v174, v174, v62
	v_add_f32_e32 v175, v175, v47
	v_add_f32_e32 v174, v174, v63
	v_add_f32_e32 v175, v175, v174
	v_cmp_ge_f32_e32 vcc, s23, v175
	s_cmp_eq_u64 vcc, exec
	s_cbranch_scc0 .Lat_rare3
; #define SBAR() __builtin_amdgcn_sched_barrier(0)
; #define SLOAD(i, k0) do { sr_[i].vs = *(const bf16x8*)(Kh + (size_t)((k0) + skey) * 2048 + 64 + sc8); \
;     sr_[i].ks = *(const bf16x8*)(Kh + (size_t)((k0) + skey) * 2048 + sc8); \
;     sr_[i].ps = *(const bf16x8*)(Kp + (size_t)((k0) + pkey) * 32 + pc8); } while (0)
; #define SWRITE(bb, i) do { *(bf16x8*)(V_lds + (bb) * AT_SHMV + vst) = sr_[i].vs; \
;     *(bf16x8*)(K_lds + (bb) * AT_SHMK + kst) = sr_[i].ks; \
;     *(bf16x8*)(K_lds + (bb) * AT_SHMK + pst) = sr_[i].ps; } while (0)
; #define SWAIT() asm volatile("s_waitcnt vmcnt(3)" ::: "memory")
; #define RESC(a) do { if (__any((a) < 1.f)) { if (hi == 0) al_l[r32] = (a); asm volatile("s_waitcnt lgkmcnt(0)" ::: "memory"); \
;     _Pragma("unroll") for (int dd = 0; dd < 2; ++dd) _Pragma("unroll") for (int r = 0; r < 16; ++r) o[dd][r] *= al_l[crow(r, hi)]; } } while (0)
; __device__ void phase_attn(const Params& p, char* lds) {
;     ...
;     for (int j = 1; j + 1 < NT; j += 2) {
;       SBAR(); at_qkt(pB0, pB1, K_lds + AT_SHMK, qr, r32, hi, -m_reg);
;       at_finishSM(pA0, pA1, alA, l_reg, pa0, pa1, pa2, pa3); SBAR();
;       SLOAD(1, (j + 2) * 64); SBAR();
;       pv_d0(o, vb0, pa0, pa1, pa2, pa3); at_partialSM(pB0, pB1, m_reg, alB, false);
;       __syncthreads(); SWAIT(); SWRITE(0, 0);
;       RESC(alB); __syncthreads();
;       SBAR(); at_qkt(pA0, pA1, K_lds, qr, r32, hi, -m_reg);
;       at_finishSM(pB0, pB1, alB, l_reg, pa0, pa1, pa2, pa3); SBAR();
;       if (j + 3 < NT) SLOAD(0, (j + 3) * 64); SBAR();
;       pv_d0(o, vb0 + AT_SHMV, pa0, pa1, pa2, pa3); at_partialSM(pA0, pA1, m_reg, alA, false);
;       __syncthreads(); SWAIT(); SWRITE(1, 1);
;       RESC(alA); __syncthreads();
;     }
;     SBAR(); at_qkt(pB0, pB1, K_lds + AT_SHMK, qr, r32, hi, -m_reg);
;     at_finishSM(pA0, pA1, alA, l_reg, pa0, pa1, pa2, pa3); SBAR();
.Lat_rare3_back:
	v_add_f32_e32 v173, v173, v175
	v_cvt_pk_bf16_f32 v104, v32, v33
	v_cvt_pk_bf16_f32 v105, v34, v35
	v_cvt_pk_bf16_f32 v106, v36, v37
	v_cvt_pk_bf16_f32 v107, v38, v39
	v_cvt_pk_bf16_f32 v108, v40, v41
	v_cvt_pk_bf16_f32 v109, v42, v43
	v_cvt_pk_bf16_f32 v110, v44, v45
	v_cvt_pk_bf16_f32 v111, v46, v47
	v_cvt_pk_bf16_f32 v112, v48, v49
	v_cvt_pk_bf16_f32 v113, v50, v51
	v_cvt_pk_bf16_f32 v114, v52, v53
	v_cvt_pk_bf16_f32 v115, v54, v55
	v_cvt_pk_bf16_f32 v116, v56, v57
	v_cvt_pk_bf16_f32 v117, v58, v59
	v_cvt_pk_bf16_f32 v118, v60, v61
	v_cvt_pk_bf16_f32 v119, v62, v63
	ds_read_b128 v[184:187], v170 offset:13312
	ds_read_b128 v[188:191], v170 offset:19968
	ds_read_b128 v[192:195], v170 offset:13344
	ds_read_b128 v[196:199], v170 offset:20000
	s_barrier
	s_sub_u32 s13, s13, 1
	s_cmp_lg_u32 s13, 0
	s_cbranch_scc1 .Lat_loop
	ds_read_b128 v[200:203], v170 offset:13376
	ds_read_b128 v[204:207], v170 offset:20032
	s_waitcnt lgkmcnt(5)
	v_mfma_f32_32x32x16_bf16 v[32:47], v[184:187], v[80:83], v[64:79]
	s_waitcnt lgkmcnt(4)
	v_mfma_f32_32x32x16_bf16 v[48:63], v[188:191], v[80:83], v[64:79]
	ds_read_b128 v[208:211], v170 offset:13408
	ds_read_b128 v[212:215], v170 offset:20064
	s_waitcnt lgkmcnt(5)
	v_mfma_f32_32x32x16_bf16 v[32:47], v[192:195], v[84:87], v[32:47]
	s_waitcnt lgkmcnt(4)
	v_mfma_f32_32x32x16_bf16 v[48:63], v[196:199], v[84:87], v[48:63]
	ds_read_b128 v[184:187], v170 offset:13440
	ds_read_b128 v[188:191], v170 offset:20096
	s_waitcnt lgkmcnt(5)
	v_mfma_f32_32x32x16_bf16 v[32:47], v[200:203], v[88:91], v[32:47]
	s_waitcnt lgkmcnt(4)
	v_mfma_f32_32x32x16_bf16 v[48:63], v[204:207], v[88:91], v[48:63]
	ds_read_b128 v[192:195], v170 offset:13472
	ds_read_b128 v[196:199], v170 offset:20128
	s_waitcnt lgkmcnt(5)
	v_mfma_f32_32x32x16_bf16 v[32:47], v[208:211], v[92:95], v[32:47]
	s_waitcnt lgkmcnt(4)
	v_mfma_f32_32x32x16_bf16 v[48:63], v[212:215], v[92:95], v[48:63]
	ds_read_b64_tr_b16 v[148:149], v171 offset:0
	ds_read_b64_tr_b16 v[150:151], v171 offset:2048
	ds_read_b64_tr_b16 v[152:153], v171 offset:4096
	ds_read_b64_tr_b16 v[154:155], v171 offset:6144
	s_waitcnt lgkmcnt(7)
	v_mfma_f32_32x32x16_bf16 v[32:47], v[184:187], v[96:99], v[32:47]
	s_waitcnt lgkmcnt(6)
	v_mfma_f32_32x32x16_bf16 v[48:63], v[188:191], v[96:99], v[48:63]
	ds_read_b64_tr_b16 v[156:157], v171 offset:8192
	ds_read_b64_tr_b16 v[158:159], v171 offset:10240
	ds_read_b64_tr_b16 v[216:217], v171 offset:12288
	ds_read_b64_tr_b16 v[218:219], v171 offset:14336
	s_waitcnt lgkmcnt(9)
	v_mfma_f32_32x32x16_bf16 v[32:47], v[192:195], v[100:103], v[32:47]
	s_waitcnt lgkmcnt(8)
	v_mfma_f32_32x32x16_bf16 v[48:63], v[196:199], v[100:103], v[48:63]
	ds_read_b64_tr_b16 v[220:221], v171 offset:512
	ds_read_b64_tr_b16 v[222:223], v171 offset:2560
	ds_read_b64_tr_b16 v[224:225], v171 offset:4608
	ds_read_b64_tr_b16 v[226:227], v171 offset:6656
	s_waitcnt lgkmcnt(10)
	v_mfma_f32_32x32x16_bf16 v[0:15], v[104:107], v[148:151], v[0:15]
	s_waitcnt lgkmcnt(8)
	v_mfma_f32_32x32x16_bf16 v[0:15], v[108:111], v[152:155], v[0:15]
	ds_read_b64_tr_b16 v[236:237], v171 offset:8704
	ds_read_b64_tr_b16 v[238:239], v171 offset:10752
	ds_read_b64_tr_b16 v[240:241], v171 offset:12800
	ds_read_b64_tr_b16 v[242:243], v171 offset:14848
	s_waitcnt lgkmcnt(10)
	v_mfma_f32_32x32x16_bf16 v[0:15], v[112:115], v[156:159], v[0:15]
	s_waitcnt lgkmcnt(8)
	v_mfma_f32_32x32x16_bf16 v[0:15], v[116:119], v[216:219], v[0:15]
	s_waitcnt lgkmcnt(6)
	v_mfma_f32_32x32x16_bf16 v[16:31], v[104:107], v[220:223], v[16:31]
	s_waitcnt lgkmcnt(4)
	v_mfma_f32_32x32x16_bf16 v[16:31], v[108:111], v[224:227], v[16:31]
	s_waitcnt lgkmcnt(2)
	v_mfma_f32_32x32x16_bf16 v[16:31], v[112:115], v[236:239], v[16:31]
	s_waitcnt lgkmcnt(0)
	v_mfma_f32_32x32x16_bf16 v[16:31], v[116:119], v[240:243], v[16:31]
	s_barrier
	s_waitcnt vmcnt(0)
	ds_write_b128 v167, v[120:123] offset:39936
	ds_write_b128 v131, v[124:127] offset:49152
	ds_write_b128 v169, v[132:135] offset:39936
	v_exp_f32_e32 v32, v32
	v_exp_f32_e32 v48, v48
	v_exp_f32_e32 v33, v33
	v_exp_f32_e32 v49, v49
	v_exp_f32_e32 v34, v34
	v_exp_f32_e32 v50, v50
	v_exp_f32_e32 v35, v35
	v_exp_f32_e32 v51, v51
	v_exp_f32_e32 v36, v36
	v_exp_f32_e32 v52, v52
	v_exp_f32_e32 v37, v37
	v_exp_f32_e32 v53, v53
	v_exp_f32_e32 v38, v38
	v_exp_f32_e32 v54, v54
	v_exp_f32_e32 v39, v39
	v_exp_f32_e32 v55, v55
	v_exp_f32_e32 v40, v40
	v_exp_f32_e32 v56, v56
	v_exp_f32_e32 v41, v41
	v_exp_f32_e32 v57, v57
	v_exp_f32_e32 v42, v42
	v_exp_f32_e32 v58, v58
	v_exp_f32_e32 v43, v43
	v_exp_f32_e32 v59, v59
	v_exp_f32_e32 v44, v44
	v_exp_f32_e32 v60, v60
	v_exp_f32_e32 v45, v45
	v_exp_f32_e32 v61, v61
	v_exp_f32_e32 v46, v46
	v_exp_f32_e32 v62, v62
	v_exp_f32_e32 v47, v47
	v_exp_f32_e32 v63, v63
	s_waitcnt lgkmcnt(0)
	v_add_f32_e32 v175, v32, v33
	v_add_f32_e32 v174, v48, v49
	v_add_f32_e32 v175, v175, v34
	v_add_f32_e32 v174, v174, v50
	v_add_f32_e32 v175, v175, v35
	v_add_f32_e32 v174, v174, v51
	v_add_f32_e32 v175, v175, v36
	v_add_f32_e32 v174, v174, v52
	v_add_f32_e32 v175, v175, v37
	v_add_f32_e32 v174, v174, v53
	v_add_f32_e32 v175, v175, v38
	v_add_f32_e32 v174, v174, v54
	v_add_f32_e32 v175, v175, v39
	v_add_f32_e32 v174, v174, v55
	v_add_f32_e32 v175, v175, v40
	v_add_f32_e32 v174, v174, v56
	v_add_f32_e32 v175, v175, v41
	v_add_f32_e32 v174, v174, v57
	v_add_f32_e32 v175, v175, v42
	v_add_f32_e32 v174, v174, v58
	v_add_f32_e32 v175, v175, v43
	v_add_f32_e32 v174, v174, v59
	v_add_f32_e32 v175, v175, v44
	v_add_f32_e32 v174, v174, v60
	v_add_f32_e32 v175, v175, v45
	v_add_f32_e32 v174, v174, v61
	v_add_f32_e32 v175, v175, v46
	v_add_f32_e32 v174, v174, v62
	v_add_f32_e32 v175, v175, v47
	v_add_f32_e32 v174, v174, v63
	v_add_f32_e32 v175, v175, v174
	v_cmp_ge_f32_e32 vcc, s23, v175
	s_cmp_eq_u64 vcc, exec
	s_cbranch_scc0 .Lat_rare_t129
; #define SBAR() __builtin_amdgcn_sched_barrier(0)
; #define RESC(a) do { if (__any((a) < 1.f)) { if (hi == 0) al_l[r32] = (a); asm volatile("s_waitcnt lgkmcnt(0)" ::: "memory"); \
;     _Pragma("unroll") for (int dd = 0; dd < 2; ++dd) _Pragma("unroll") for (int r = 0; r < 16; ++r) o[dd][r] *= al_l[crow(r, hi)]; } } while (0)
; __device__ void phase_attn(const Params& p, char* lds) {
;     ...
;     SBAR(); at_qkt(pB0, pB1, K_lds + AT_SHMK, qr, r32, hi, -m_reg);
;     at_finishSM(pA0, pA1, alA, l_reg, pa0, pa1, pa2, pa3); SBAR();
;     pv_d0(o, vb0, pa0, pa1, pa2, pa3); at_partialSM(pB0, pB1, m_reg, alB, false);
;     __syncthreads(); RESC(alB);
;     at_finishSM(pB0, pB1, alB, l_reg, pa0, pa1, pa2, pa3); SBAR();
.Lat_rare_t129_back:
	v_add_f32_e32 v173, v173, v175
	v_cvt_pk_bf16_f32 v104, v32, v33
	v_cvt_pk_bf16_f32 v105, v34, v35
	v_cvt_pk_bf16_f32 v106, v36, v37
	v_cvt_pk_bf16_f32 v107, v38, v39
	v_cvt_pk_bf16_f32 v108, v40, v41
	v_cvt_pk_bf16_f32 v109, v42, v43
	v_cvt_pk_bf16_f32 v110, v44, v45
	v_cvt_pk_bf16_f32 v111, v46, v47
	v_cvt_pk_bf16_f32 v112, v48, v49
	v_cvt_pk_bf16_f32 v113, v50, v51
	v_cvt_pk_bf16_f32 v114, v52, v53
	v_cvt_pk_bf16_f32 v115, v54, v55
	v_cvt_pk_bf16_f32 v116, v56, v57
	v_cvt_pk_bf16_f32 v117, v58, v59
	v_cvt_pk_bf16_f32 v118, v60, v61
	v_cvt_pk_bf16_f32 v119, v62, v63
	ds_read_b128 v[184:187], v170 offset:26624
	ds_read_b128 v[188:191], v170 offset:33280
	ds_read_b128 v[192:195], v170 offset:26656
	ds_read_b128 v[196:199], v170 offset:33312
	s_barrier
	ds_read_b128 v[200:203], v170 offset:26688
	ds_read_b128 v[204:207], v170 offset:33344
	s_waitcnt lgkmcnt(5)
	v_mfma_f32_32x32x16_bf16 v[32:47], v[184:187], v[80:83], v[64:79]
	s_waitcnt lgkmcnt(4)
	v_mfma_f32_32x32x16_bf16 v[48:63], v[188:191], v[80:83], v[64:79]
	ds_read_b128 v[208:211], v170 offset:26720
	ds_read_b128 v[212:215], v170 offset:33376
	s_waitcnt lgkmcnt(5)
	v_mfma_f32_32x32x16_bf16 v[32:47], v[192:195], v[84:87], v[32:47]
	s_waitcnt lgkmcnt(4)
	v_mfma_f32_32x32x16_bf16 v[48:63], v[196:199], v[84:87], v[48:63]
	ds_read_b128 v[184:187], v170 offset:26752
	ds_read_b128 v[188:191], v170 offset:33408
	s_waitcnt lgkmcnt(5)
	v_mfma_f32_32x32x16_bf16 v[32:47], v[200:203], v[88:91], v[32:47]
	s_waitcnt lgkmcnt(4)
	v_mfma_f32_32x32x16_bf16 v[48:63], v[204:207], v[88:91], v[48:63]
	ds_read_b128 v[192:195], v170 offset:26784
	ds_read_b128 v[196:199], v170 offset:33440
	s_waitcnt lgkmcnt(5)
	v_mfma_f32_32x32x16_bf16 v[32:47], v[208:211], v[92:95], v[32:47]
	s_waitcnt lgkmcnt(4)
	v_mfma_f32_32x32x16_bf16 v[48:63], v[212:215], v[92:95], v[48:63]
	ds_read_b64_tr_b16 v[148:149], v171 offset:16384
	ds_read_b64_tr_b16 v[150:151], v171 offset:18432
	ds_read_b64_tr_b16 v[152:153], v171 offset:20480
	ds_read_b64_tr_b16 v[154:155], v171 offset:22528
	s_waitcnt lgkmcnt(7)
	v_mfma_f32_32x32x16_bf16 v[32:47], v[184:187], v[96:99], v[32:47]
	s_waitcnt lgkmcnt(6)
	v_mfma_f32_32x32x16_bf16 v[48:63], v[188:191], v[96:99], v[48:63]
	ds_read_b64_tr_b16 v[156:157], v171 offset:24576
	ds_read_b64_tr_b16 v[158:159], v171 offset:26624
	ds_read_b64_tr_b16 v[216:217], v171 offset:28672
	ds_read_b64_tr_b16 v[218:219], v171 offset:30720
	s_waitcnt lgkmcnt(9)
	v_mfma_f32_32x32x16_bf16 v[32:47], v[192:195], v[100:103], v[32:47]
	s_waitcnt lgkmcnt(8)
	v_mfma_f32_32x32x16_bf16 v[48:63], v[196:199], v[100:103], v[48:63]
	ds_read_b64_tr_b16 v[220:221], v171 offset:16896
	ds_read_b64_tr_b16 v[222:223], v171 offset:18944
	ds_read_b64_tr_b16 v[224:225], v171 offset:20992
	ds_read_b64_tr_b16 v[226:227], v171 offset:23040
	s_waitcnt lgkmcnt(10)
	v_mfma_f32_32x32x16_bf16 v[0:15], v[104:107], v[148:151], v[0:15]
	s_waitcnt lgkmcnt(8)
	v_mfma_f32_32x32x16_bf16 v[0:15], v[108:111], v[152:155], v[0:15]
	ds_read_b64_tr_b16 v[236:237], v171 offset:25088
	ds_read_b64_tr_b16 v[238:239], v171 offset:27136
	ds_read_b64_tr_b16 v[240:241], v171 offset:29184
	ds_read_b64_tr_b16 v[242:243], v171 offset:31232
	s_waitcnt lgkmcnt(10)
	v_mfma_f32_32x32x16_bf16 v[0:15], v[112:115], v[156:159], v[0:15]
	s_waitcnt lgkmcnt(8)
	v_mfma_f32_32x32x16_bf16 v[0:15], v[116:119], v[216:219], v[0:15]
	s_waitcnt lgkmcnt(6)
	v_mfma_f32_32x32x16_bf16 v[16:31], v[104:107], v[220:223], v[16:31]
	s_waitcnt lgkmcnt(4)
	v_mfma_f32_32x32x16_bf16 v[16:31], v[108:111], v[224:227], v[16:31]
	s_waitcnt lgkmcnt(2)
	v_mfma_f32_32x32x16_bf16 v[16:31], v[112:115], v[236:239], v[16:31]
	s_waitcnt lgkmcnt(0)
	v_mfma_f32_32x32x16_bf16 v[16:31], v[116:119], v[240:243], v[16:31]
	s_barrier
	v_exp_f32_e32 v32, v32
	v_exp_f32_e32 v48, v48
	v_exp_f32_e32 v33, v33
	v_exp_f32_e32 v49, v49
	v_exp_f32_e32 v34, v34
	v_exp_f32_e32 v50, v50
	v_exp_f32_e32 v35, v35
	v_exp_f32_e32 v51, v51
	v_exp_f32_e32 v36, v36
	v_exp_f32_e32 v52, v52
	v_exp_f32_e32 v37, v37
	v_exp_f32_e32 v53, v53
	v_exp_f32_e32 v38, v38
	v_exp_f32_e32 v54, v54
	v_exp_f32_e32 v39, v39
	v_exp_f32_e32 v55, v55
	v_exp_f32_e32 v40, v40
	v_exp_f32_e32 v56, v56
	v_exp_f32_e32 v41, v41
	v_exp_f32_e32 v57, v57
	v_exp_f32_e32 v42, v42
	v_exp_f32_e32 v58, v58
	v_exp_f32_e32 v43, v43
	v_exp_f32_e32 v59, v59
	v_exp_f32_e32 v44, v44
	v_exp_f32_e32 v60, v60
	v_exp_f32_e32 v45, v45
	v_exp_f32_e32 v61, v61
	v_exp_f32_e32 v46, v46
	v_exp_f32_e32 v62, v62
	v_exp_f32_e32 v47, v47
	v_exp_f32_e32 v63, v63
	v_add_f32_e32 v175, v32, v33
	v_add_f32_e32 v174, v48, v49
	v_add_f32_e32 v175, v175, v34
	v_add_f32_e32 v174, v174, v50
	v_add_f32_e32 v175, v175, v35
	v_add_f32_e32 v174, v174, v51
	v_add_f32_e32 v175, v175, v36
	v_add_f32_e32 v174, v174, v52
	v_add_f32_e32 v175, v175, v37
	v_add_f32_e32 v174, v174, v53
	v_add_f32_e32 v175, v175, v38
	v_add_f32_e32 v174, v174, v54
	v_add_f32_e32 v175, v175, v39
	v_add_f32_e32 v174, v174, v55
	v_add_f32_e32 v175, v175, v40
	v_add_f32_e32 v174, v174, v56
	v_add_f32_e32 v175, v175, v41
	v_add_f32_e32 v174, v174, v57
	v_add_f32_e32 v175, v175, v42
	v_add_f32_e32 v174, v174, v58
	v_add_f32_e32 v175, v175, v43
	v_add_f32_e32 v174, v174, v59
	v_add_f32_e32 v175, v175, v44
	v_add_f32_e32 v174, v174, v60
	v_add_f32_e32 v175, v175, v45
	v_add_f32_e32 v174, v174, v61
	v_add_f32_e32 v175, v175, v46
	v_add_f32_e32 v174, v174, v62
	v_add_f32_e32 v175, v175, v47
	v_add_f32_e32 v174, v174, v63
	v_add_f32_e32 v175, v175, v174
	v_cmp_ge_f32_e32 vcc, s23, v175
	s_cmp_eq_u64 vcc, exec
	s_cbranch_scc0 .Lat_rare_t130
; #define SBAR() __builtin_amdgcn_sched_barrier(0)
; #define RESC(a) do { if (__any((a) < 1.f)) { if (hi == 0) al_l[r32] = (a); asm volatile("s_waitcnt lgkmcnt(0)" ::: "memory"); \
;     _Pragma("unroll") for (int dd = 0; dd < 2; ++dd) _Pragma("unroll") for (int r = 0; r < 16; ++r) o[dd][r] *= al_l[crow(r, hi)]; } } while (0)
; __device__ void phase_attn(const Params& p, char* lds) {
;     ...
;     pv_d0(o, vb0, pa0, pa1, pa2, pa3); at_partialSM(pB0, pB1, m_reg, alB, false);
;     __syncthreads(); RESC(alB);
;     at_finishSM(pB0, pB1, alB, l_reg, pa0, pa1, pa2, pa3); SBAR();
;     pv_d0(o, vb0 + AT_SHMV, pa0, pa1, pa2, pa3);
.Lat_rare_t130_back:
	v_add_f32_e32 v173, v173, v175
	v_cvt_pk_bf16_f32 v104, v32, v33
	v_cvt_pk_bf16_f32 v105, v34, v35
	v_cvt_pk_bf16_f32 v106, v36, v37
	v_cvt_pk_bf16_f32 v107, v38, v39
	v_cvt_pk_bf16_f32 v108, v40, v41
	v_cvt_pk_bf16_f32 v109, v42, v43
	v_cvt_pk_bf16_f32 v110, v44, v45
	v_cvt_pk_bf16_f32 v111, v46, v47
	v_cvt_pk_bf16_f32 v112, v48, v49
	v_cvt_pk_bf16_f32 v113, v50, v51
	v_cvt_pk_bf16_f32 v114, v52, v53
	v_cvt_pk_bf16_f32 v115, v54, v55
	v_cvt_pk_bf16_f32 v116, v56, v57
	v_cvt_pk_bf16_f32 v117, v58, v59
	v_cvt_pk_bf16_f32 v118, v60, v61
	v_cvt_pk_bf16_f32 v119, v62, v63
	ds_read_b128 v[184:187], v170 offset:39936
	ds_read_b128 v[188:191], v170 offset:46592
	ds_read_b128 v[192:195], v170 offset:39968
	ds_read_b128 v[196:199], v170 offset:46624
	s_barrier
	ds_read_b128 v[200:203], v170 offset:40000
	ds_read_b128 v[204:207], v170 offset:46656
	s_waitcnt lgkmcnt(5)
	v_mfma_f32_32x32x16_bf16 v[32:47], v[184:187], v[80:83], v[64:79]
	s_waitcnt lgkmcnt(4)
	v_mfma_f32_32x32x16_bf16 v[48:63], v[188:191], v[80:83], v[64:79]
	ds_read_b128 v[208:211], v170 offset:40032
	ds_read_b128 v[212:215], v170 offset:46688
	s_waitcnt lgkmcnt(5)
	v_mfma_f32_32x32x16_bf16 v[32:47], v[192:195], v[84:87], v[32:47]
	s_waitcnt lgkmcnt(4)
	v_mfma_f32_32x32x16_bf16 v[48:63], v[196:199], v[84:87], v[48:63]
	ds_read_b128 v[184:187], v170 offset:40064
	ds_read_b128 v[188:191], v170 offset:46720
	s_waitcnt lgkmcnt(5)
	v_mfma_f32_32x32x16_bf16 v[32:47], v[200:203], v[88:91], v[32:47]
	s_waitcnt lgkmcnt(4)
	v_mfma_f32_32x32x16_bf16 v[48:63], v[204:207], v[88:91], v[48:63]
	ds_read_b128 v[192:195], v170 offset:40096
	ds_read_b128 v[196:199], v170 offset:46752
	s_waitcnt lgkmcnt(5)
	v_mfma_f32_32x32x16_bf16 v[32:47], v[208:211], v[92:95], v[32:47]
	s_waitcnt lgkmcnt(4)
	v_mfma_f32_32x32x16_bf16 v[48:63], v[212:215], v[92:95], v[48:63]
	ds_read_b64_tr_b16 v[148:149], v171 offset:32768
	ds_read_b64_tr_b16 v[150:151], v171 offset:34816
	ds_read_b64_tr_b16 v[152:153], v171 offset:36864
	ds_read_b64_tr_b16 v[154:155], v171 offset:38912
	s_waitcnt lgkmcnt(7)
	v_mfma_f32_32x32x16_bf16 v[32:47], v[184:187], v[96:99], v[32:47]
	s_waitcnt lgkmcnt(6)
	v_mfma_f32_32x32x16_bf16 v[48:63], v[188:191], v[96:99], v[48:63]
	ds_read_b64_tr_b16 v[156:157], v171 offset:40960
	ds_read_b64_tr_b16 v[158:159], v171 offset:43008
	ds_read_b64_tr_b16 v[216:217], v171 offset:45056
	ds_read_b64_tr_b16 v[218:219], v171 offset:47104
	s_waitcnt lgkmcnt(9)
	v_mfma_f32_32x32x16_bf16 v[32:47], v[192:195], v[100:103], v[32:47]
	s_waitcnt lgkmcnt(8)
	v_mfma_f32_32x32x16_bf16 v[48:63], v[196:199], v[100:103], v[48:63]
	ds_read_b64_tr_b16 v[220:221], v171 offset:33280
	ds_read_b64_tr_b16 v[222:223], v171 offset:35328
	ds_read_b64_tr_b16 v[224:225], v171 offset:37376
	ds_read_b64_tr_b16 v[226:227], v171 offset:39424
	s_waitcnt lgkmcnt(10)
	v_mfma_f32_32x32x16_bf16 v[0:15], v[104:107], v[148:151], v[0:15]
	s_waitcnt lgkmcnt(8)
	v_mfma_f32_32x32x16_bf16 v[0:15], v[108:111], v[152:155], v[0:15]
	ds_read_b64_tr_b16 v[236:237], v171 offset:41472
	ds_read_b64_tr_b16 v[238:239], v171 offset:43520
	ds_read_b64_tr_b16 v[240:241], v171 offset:45568
	ds_read_b64_tr_b16 v[242:243], v171 offset:47616
	s_waitcnt lgkmcnt(10)
	v_mfma_f32_32x32x16_bf16 v[0:15], v[112:115], v[156:159], v[0:15]
	s_waitcnt lgkmcnt(8)
	v_mfma_f32_32x32x16_bf16 v[0:15], v[116:119], v[216:219], v[0:15]
	s_waitcnt lgkmcnt(6)
	v_mfma_f32_32x32x16_bf16 v[16:31], v[104:107], v[220:223], v[16:31]
	s_waitcnt lgkmcnt(4)
	v_mfma_f32_32x32x16_bf16 v[16:31], v[108:111], v[224:227], v[16:31]
	s_waitcnt lgkmcnt(2)
	v_mfma_f32_32x32x16_bf16 v[16:31], v[112:115], v[236:239], v[16:31]
	s_waitcnt lgkmcnt(0)
	v_mfma_f32_32x32x16_bf16 v[16:31], v[116:119], v[240:243], v[16:31]
	s_barrier
	v_exp_f32_e32 v32, v32
	v_exp_f32_e32 v48, v48
	v_exp_f32_e32 v33, v33
	v_exp_f32_e32 v49, v49
	v_exp_f32_e32 v34, v34
	v_exp_f32_e32 v50, v50
	v_exp_f32_e32 v35, v35
	v_exp_f32_e32 v51, v51
	v_exp_f32_e32 v36, v36
	v_exp_f32_e32 v52, v52
	v_exp_f32_e32 v37, v37
	v_exp_f32_e32 v53, v53
	v_exp_f32_e32 v38, v38
	v_exp_f32_e32 v54, v54
	v_exp_f32_e32 v39, v39
	v_exp_f32_e32 v55, v55
	v_exp_f32_e32 v40, v40
	v_exp_f32_e32 v56, v56
	v_exp_f32_e32 v41, v41
	v_exp_f32_e32 v57, v57
	v_exp_f32_e32 v42, v42
	v_exp_f32_e32 v58, v58
	v_exp_f32_e32 v43, v43
	v_exp_f32_e32 v59, v59
	v_exp_f32_e32 v44, v44
	v_exp_f32_e32 v60, v60
	v_exp_f32_e32 v45, v45
	v_exp_f32_e32 v61, v61
	v_exp_f32_e32 v46, v46
	v_exp_f32_e32 v62, v62
	v_exp_f32_e32 v47, v47
	v_exp_f32_e32 v63, v63
	v_add_f32_e32 v175, v32, v33
	v_add_f32_e32 v174, v48, v49
	v_add_f32_e32 v175, v175, v34
	v_add_f32_e32 v174, v174, v50
	v_add_f32_e32 v175, v175, v35
	v_add_f32_e32 v174, v174, v51
	v_add_f32_e32 v175, v175, v36
	v_add_f32_e32 v174, v174, v52
	v_add_f32_e32 v175, v175, v37
	v_add_f32_e32 v174, v174, v53
	v_add_f32_e32 v175, v175, v38
	v_add_f32_e32 v174, v174, v54
	v_add_f32_e32 v175, v175, v39
	v_add_f32_e32 v174, v174, v55
	v_add_f32_e32 v175, v175, v40
	v_add_f32_e32 v174, v174, v56
	v_add_f32_e32 v175, v175, v41
	v_add_f32_e32 v174, v174, v57
	v_add_f32_e32 v175, v175, v42
	v_add_f32_e32 v174, v174, v58
	v_add_f32_e32 v175, v175, v43
	v_add_f32_e32 v174, v174, v59
	v_add_f32_e32 v175, v175, v44
	v_add_f32_e32 v174, v174, v60
	v_add_f32_e32 v175, v175, v45
	v_add_f32_e32 v174, v174, v61
	v_add_f32_e32 v175, v175, v46
	v_add_f32_e32 v174, v174, v62
	v_add_f32_e32 v175, v175, v47
	v_add_f32_e32 v174, v174, v63
	v_add_f32_e32 v175, v175, v174
	v_cmp_ge_f32_e32 vcc, s23, v175
	s_cmp_eq_u64 vcc, exec
	s_cbranch_scc0 .Lat_rare_t131
; #define SBAR() __builtin_amdgcn_sched_barrier(0)
; __device__ void phase_attn(const Params& p, char* lds) {
;     ...
;     at_finishSM(pB0, pB1, alB, l_reg, pa0, pa1, pa2, pa3); SBAR();
;     pv_d0(o, vb0 + AT_SHMV, pa0, pa1, pa2, pa3);
.Lat_rare_t131_back:
	v_add_f32_e32 v173, v173, v175
	v_cvt_pk_bf16_f32 v104, v32, v33
	v_cvt_pk_bf16_f32 v105, v34, v35
	v_cvt_pk_bf16_f32 v106, v36, v37
	v_cvt_pk_bf16_f32 v107, v38, v39
	v_cvt_pk_bf16_f32 v108, v40, v41
	v_cvt_pk_bf16_f32 v109, v42, v43
	v_cvt_pk_bf16_f32 v110, v44, v45
	v_cvt_pk_bf16_f32 v111, v46, v47
	v_cvt_pk_bf16_f32 v112, v48, v49
	v_cvt_pk_bf16_f32 v113, v50, v51
	v_cvt_pk_bf16_f32 v114, v52, v53
	v_cvt_pk_bf16_f32 v115, v54, v55
	v_cvt_pk_bf16_f32 v116, v56, v57
	v_cvt_pk_bf16_f32 v117, v58, v59
	v_cvt_pk_bf16_f32 v118, v60, v61
	v_cvt_pk_bf16_f32 v119, v62, v63
	s_barrier
	ds_read_b64_tr_b16 v[148:149], v171 offset:49152
	ds_read_b64_tr_b16 v[150:151], v171 offset:51200
	ds_read_b64_tr_b16 v[152:153], v171 offset:53248
	ds_read_b64_tr_b16 v[154:155], v171 offset:55296
	ds_read_b64_tr_b16 v[156:157], v171 offset:57344
	ds_read_b64_tr_b16 v[158:159], v171 offset:59392
	ds_read_b64_tr_b16 v[216:217], v171 offset:61440
	ds_read_b64_tr_b16 v[218:219], v171 offset:63488
	ds_read_b64_tr_b16 v[220:221], v171 offset:49664
	ds_read_b64_tr_b16 v[222:223], v171 offset:51712
	ds_read_b64_tr_b16 v[224:225], v171 offset:53760
	ds_read_b64_tr_b16 v[226:227], v171 offset:55808
	s_waitcnt lgkmcnt(10)
	v_mfma_f32_32x32x16_bf16 v[0:15], v[104:107], v[148:151], v[0:15]
	s_waitcnt lgkmcnt(8)
	v_mfma_f32_32x32x16_bf16 v[0:15], v[108:111], v[152:155], v[0:15]
	ds_read_b64_tr_b16 v[236:237], v171 offset:57856
	ds_read_b64_tr_b16 v[238:239], v171 offset:59904
	ds_read_b64_tr_b16 v[240:241], v171 offset:61952
	ds_read_b64_tr_b16 v[242:243], v171 offset:64000
	s_waitcnt lgkmcnt(10)
	v_mfma_f32_32x32x16_bf16 v[0:15], v[112:115], v[156:159], v[0:15]
	s_waitcnt lgkmcnt(8)
	v_mfma_f32_32x32x16_bf16 v[0:15], v[116:119], v[216:219], v[0:15]
	s_waitcnt lgkmcnt(6)
	v_mfma_f32_32x32x16_bf16 v[16:31], v[104:107], v[220:223], v[16:31]
	s_waitcnt lgkmcnt(4)
	v_mfma_f32_32x32x16_bf16 v[16:31], v[108:111], v[224:227], v[16:31]
	s_waitcnt lgkmcnt(2)
	v_mfma_f32_32x32x16_bf16 v[16:31], v[112:115], v[236:239], v[16:31]
	s_waitcnt lgkmcnt(0)
	v_mfma_f32_32x32x16_bf16 v[16:31], v[116:119], v[240:243], v[16:31]
	s_cmp_lg_u32 s15, 0
	s_cbranch_scc1 .Lat_nobal
	s_barrier

; #define MFMA(a, b, c) __builtin_amdgcn_mfma_f32_32x32x16_bf16((a), (b), (c), 0, 0, 0)
; __device__ __forceinline__ void at_partialSM(f32x16& p0, f32x16& p1, float& m_reg, float& alpha, bool force) {
;   float pm = p0[0];
; #pragma unroll
;   for (int r = 1; r < 16; ++r) pm = fmaxf(pm, p0[r]);
; #pragma unroll
;   for (int r = 0; r < 16; ++r) pm = fmaxf(pm, p1[r]);
;   { auto rr = __builtin_amdgcn_permlane32_swap(__float_as_uint(pm), __float_as_uint(pm), false, false);
;     pm = fmaxf(__uint_as_float(rr[0]), __uint_as_float(rr[1])); }
;   if (__builtin_expect(!force && __all(pm <= AT_THR * 1.4426950408889634f), 1)) { alpha = 1.f; }
;   else {
;     const float dlt = force ? pm : fmaxf(pm, 0.f);
;     alpha = force ? 1.f : __builtin_amdgcn_exp2f(-dlt); m_reg += dlt;
; #pragma unroll
;     for (int r = 0; r < 16; ++r) { p0[r] -= dlt; p1[r] -= dlt; }
;   }
; #pragma unroll
;   for (int r = 0; r < 16; ++r) p0[r] = __builtin_amdgcn_exp2f(p0[r]);
; }
; __device__ __forceinline__ void at_qkt(f32x16& p0, f32x16& p1, const char* Ks, const bf16x8* qr, int r32, int hi, float negm) {
; #pragma unroll
;   for (int r = 0; r < 16; ++r) { p0[r] = negm; p1[r] = negm; }
; #pragma unroll
;   for (int d0 = 0; d0 < 6; ++d0) {
;     const bf16x8 b0 = *(const bf16x8*)(Ks + r32 * AT_KROW + d0 * 32 + hi * 16);
;     const bf16x8 b1 = *(const bf16x8*)(Ks + (32 + r32) * AT_KROW + d0 * 32 + hi * 16);
;     p0 = MFMA(b0, qr[d0], p0);
;     p1 = MFMA(b1, qr[d0], p1);
;   }
; }
.Lat_rare0:
	ds_read_b128 v[184:187], v170 offset:13312
	ds_read_b128 v[188:191], v170 offset:19968
	s_waitcnt lgkmcnt(1)
	v_mfma_f32_32x32x16_bf16 v[32:47], v[184:187], v[80:83], 0
	s_waitcnt lgkmcnt(0)
	v_mfma_f32_32x32x16_bf16 v[48:63], v[188:191], v[80:83], 0
	s_nop 7
	s_nop 7
	ds_read_b128 v[184:187], v170 offset:13344
	ds_read_b128 v[188:191], v170 offset:20000
	s_waitcnt lgkmcnt(1)
	v_mfma_f32_32x32x16_bf16 v[32:47], v[184:187], v[84:87], v[32:47]
	s_waitcnt lgkmcnt(0)
	v_mfma_f32_32x32x16_bf16 v[48:63], v[188:191], v[84:87], v[48:63]
	s_nop 7
	s_nop 7
	ds_read_b128 v[184:187], v170 offset:13376
	ds_read_b128 v[188:191], v170 offset:20032
	s_waitcnt lgkmcnt(1)
	v_mfma_f32_32x32x16_bf16 v[32:47], v[184:187], v[88:91], v[32:47]
	s_waitcnt lgkmcnt(0)
	v_mfma_f32_32x32x16_bf16 v[48:63], v[188:191], v[88:91], v[48:63]
	s_nop 7
	s_nop 7
	ds_read_b128 v[184:187], v170 offset:13408
	ds_read_b128 v[188:191], v170 offset:20064
	s_waitcnt lgkmcnt(1)
	v_mfma_f32_32x32x16_bf16 v[32:47], v[184:187], v[92:95], v[32:47]
	s_waitcnt lgkmcnt(0)
	v_mfma_f32_32x32x16_bf16 v[48:63], v[188:191], v[92:95], v[48:63]
	s_nop 7
	s_nop 7
	ds_read_b128 v[184:187], v170 offset:13440
	ds_read_b128 v[188:191], v170 offset:20096
	s_waitcnt lgkmcnt(1)
	v_mfma_f32_32x32x16_bf16 v[32:47], v[184:187], v[96:99], v[32:47]
	s_waitcnt lgkmcnt(0)
	v_mfma_f32_32x32x16_bf16 v[48:63], v[188:191], v[96:99], v[48:63]
	s_nop 7
	s_nop 7
	ds_read_b128 v[184:187], v170 offset:13472
	ds_read_b128 v[188:191], v170 offset:20128
	s_waitcnt lgkmcnt(1)
	v_mfma_f32_32x32x16_bf16 v[32:47], v[184:187], v[100:103], v[32:47]
	s_waitcnt lgkmcnt(0)
	v_mfma_f32_32x32x16_bf16 v[48:63], v[188:191], v[100:103], v[48:63]
	s_nop 7
	s_nop 7
	s_nop 7
	s_nop 7
	v_max3_f32 v174, v32, v33, v34
	v_max3_f32 v175, v48, v49, v50
	v_max3_f32 v174, v174, v35, v36
	v_max3_f32 v175, v175, v51, v52
	v_max3_f32 v174, v174, v37, v38
	v_max3_f32 v175, v175, v53, v54
	v_max3_f32 v174, v174, v39, v40
	v_max3_f32 v175, v175, v55, v56
	v_max3_f32 v174, v174, v41, v42
	v_max3_f32 v175, v175, v57, v58
	v_max3_f32 v174, v174, v43, v44
	v_max3_f32 v175, v175, v59, v60
	v_max3_f32 v174, v174, v45, v46
	v_max3_f32 v175, v175, v61, v62
	v_max3_f32 v174, v174, v47, v63
	v_max_f32_e32 v174, v174, v175
	v_mov_b32_e32 v175, v174
	s_nop 1
	v_permlane32_swap_b32_e32 v174, v175
	v_max_f32_e32 v174, v174, v175
	v_sub_f32_e32 v174, v174, v172
	v_max_f32_e32 v174, 0, v174
	v_sub_f32_e32 v175, 0, v174
	v_exp_f32_e32 v181, v175
	v_add_f32_e32 v172, v172, v174
	v_sub_f32_e32 v32, v32, v172
	v_sub_f32_e32 v48, v48, v172
	v_sub_f32_e32 v33, v33, v172
	v_sub_f32_e32 v49, v49, v172
	v_sub_f32_e32 v34, v34, v172
	v_sub_f32_e32 v50, v50, v172
	v_sub_f32_e32 v35, v35, v172
	v_sub_f32_e32 v51, v51, v172
	v_sub_f32_e32 v36, v36, v172
	v_sub_f32_e32 v52, v52, v172
	v_sub_f32_e32 v37, v37, v172
	v_sub_f32_e32 v53, v53, v172
	v_sub_f32_e32 v38, v38, v172
	v_sub_f32_e32 v54, v54, v172
	v_sub_f32_e32 v39, v39, v172
	v_sub_f32_e32 v55, v55, v172
	v_sub_f32_e32 v40, v40, v172
	v_sub_f32_e32 v56, v56, v172
	v_sub_f32_e32 v41, v41, v172
	v_sub_f32_e32 v57, v57, v172
	v_sub_f32_e32 v42, v42, v172
	v_sub_f32_e32 v58, v58, v172
	v_sub_f32_e32 v43, v43, v172
	v_sub_f32_e32 v59, v59, v172
	v_sub_f32_e32 v44, v44, v172
	v_sub_f32_e32 v60, v60, v172
	v_sub_f32_e32 v45, v45, v172
	v_sub_f32_e32 v61, v61, v172
	v_sub_f32_e32 v46, v46, v172
	v_sub_f32_e32 v62, v62, v172
	v_sub_f32_e32 v47, v47, v172
	v_sub_f32_e32 v63, v63, v172
	v_sub_f32_e32 v64, 0, v172
	v_sub_f32_e32 v65, 0, v172
	v_sub_f32_e32 v66, 0, v172
	v_sub_f32_e32 v67, 0, v172
	v_sub_f32_e32 v68, 0, v172
	v_sub_f32_e32 v69, 0, v172
	v_sub_f32_e32 v70, 0, v172
	v_sub_f32_e32 v71, 0, v172
	v_sub_f32_e32 v72, 0, v172
	v_sub_f32_e32 v73, 0, v172
	v_sub_f32_e32 v74, 0, v172
	v_sub_f32_e32 v75, 0, v172
	v_sub_f32_e32 v76, 0, v172
	v_sub_f32_e32 v77, 0, v172
	v_sub_f32_e32 v78, 0, v172
	v_sub_f32_e32 v79, 0, v172
	v_mul_f32_e32 v173, v173, v181
	ds_write_b32 v244, v181
	s_waitcnt lgkmcnt(0)
	ds_read_b128 v[184:187], v245 offset:0
	ds_read_b128 v[188:191], v245 offset:32
	ds_read_b128 v[192:195], v245 offset:64
	ds_read_b128 v[196:199], v245 offset:96
	s_waitcnt lgkmcnt(0)
	v_mul_f32_e32 v0, v0, v184
	v_mul_f32_e32 v16, v16, v184
	v_mul_f32_e32 v1, v1, v185
	v_mul_f32_e32 v17, v17, v185
	v_mul_f32_e32 v2, v2, v186
	v_mul_f32_e32 v18, v18, v186
	v_mul_f32_e32 v3, v3, v187
	v_mul_f32_e32 v19, v19, v187
	v_mul_f32_e32 v4, v4, v188
	v_mul_f32_e32 v20, v20, v188
	v_mul_f32_e32 v5, v5, v189
	v_mul_f32_e32 v21, v21, v189
	v_mul_f32_e32 v6, v6, v190
	v_mul_f32_e32 v22, v22, v190
	v_mul_f32_e32 v7, v7, v191
	v_mul_f32_e32 v23, v23, v191
	v_mul_f32_e32 v8, v8, v192
	v_mul_f32_e32 v24, v24, v192
	v_mul_f32_e32 v9, v9, v193
	v_mul_f32_e32 v25, v25, v193
	v_mul_f32_e32 v10, v10, v194
	v_mul_f32_e32 v26, v26, v194
	v_mul_f32_e32 v11, v11, v195
	v_mul_f32_e32 v27, v27, v195
	v_mul_f32_e32 v12, v12, v196
	v_mul_f32_e32 v28, v28, v196
	v_mul_f32_e32 v13, v13, v197
	v_mul_f32_e32 v29, v29, v197
	v_mul_f32_e32 v14, v14, v198
	v_mul_f32_e32 v30, v30, v198
	v_mul_f32_e32 v15, v15, v199
	v_mul_f32_e32 v31, v31, v199
	v_exp_f32_e32 v32, v32
	v_exp_f32_e32 v48, v48
	v_exp_f32_e32 v33, v33
	v_exp_f32_e32 v49, v49
	v_exp_f32_e32 v34, v34
	v_exp_f32_e32 v50, v50
	v_exp_f32_e32 v35, v35
	v_exp_f32_e32 v51, v51
	v_exp_f32_e32 v36, v36
	v_exp_f32_e32 v52, v52
	v_exp_f32_e32 v37, v37
	v_exp_f32_e32 v53, v53
	v_exp_f32_e32 v38, v38
	v_exp_f32_e32 v54, v54
	v_exp_f32_e32 v39, v39
	v_exp_f32_e32 v55, v55
	v_exp_f32_e32 v40, v40
	v_exp_f32_e32 v56, v56
	v_exp_f32_e32 v41, v41
	v_exp_f32_e32 v57, v57
	v_exp_f32_e32 v42, v42
	v_exp_f32_e32 v58, v58
	v_exp_f32_e32 v43, v43
	v_exp_f32_e32 v59, v59
	v_exp_f32_e32 v44, v44
	v_exp_f32_e32 v60, v60
	v_exp_f32_e32 v45, v45
	v_exp_f32_e32 v61, v61
	v_exp_f32_e32 v46, v46
	v_exp_f32_e32 v62, v62
	v_exp_f32_e32 v47, v47
	v_exp_f32_e32 v63, v63
	v_add_f32_e32 v175, v32, v33
	v_add_f32_e32 v174, v48, v49
	v_add_f32_e32 v175, v175, v34
	v_add_f32_e32 v174, v174, v50
	v_add_f32_e32 v175, v175, v35
	v_add_f32_e32 v174, v174, v51
	v_add_f32_e32 v175, v175, v36
	v_add_f32_e32 v174, v174, v52
	v_add_f32_e32 v175, v175, v37
	v_add_f32_e32 v174, v174, v53
	v_add_f32_e32 v175, v175, v38
	v_add_f32_e32 v174, v174, v54
	v_add_f32_e32 v175, v175, v39
	v_add_f32_e32 v174, v174, v55
	v_add_f32_e32 v175, v175, v40
	v_add_f32_e32 v174, v174, v56
	v_add_f32_e32 v175, v175, v41
	v_add_f32_e32 v174, v174, v57
	v_add_f32_e32 v175, v175, v42
	v_add_f32_e32 v174, v174, v58
	v_add_f32_e32 v175, v175, v43
	v_add_f32_e32 v174, v174, v59
	v_add_f32_e32 v175, v175, v44
	v_add_f32_e32 v174, v174, v60
	v_add_f32_e32 v175, v175, v45
	v_add_f32_e32 v174, v174, v61
	v_add_f32_e32 v175, v175, v46
	v_add_f32_e32 v174, v174, v62
	v_add_f32_e32 v175, v175, v47
	v_add_f32_e32 v174, v174, v63
	v_add_f32_e32 v175, v175, v174
	s_branch .Lat_rare0_back
; #define MFMA(a, b, c) __builtin_amdgcn_mfma_f32_32x32x16_bf16((a), (b), (c), 0, 0, 0)
; __device__ __forceinline__ void at_partialSM(f32x16& p0, f32x16& p1, float& m_reg, float& alpha, bool force) {
;   float pm = p0[0];
; #pragma unroll
;   for (int r = 1; r < 16; ++r) pm = fmaxf(pm, p0[r]);
; #pragma unroll
;   for (int r = 0; r < 16; ++r) pm = fmaxf(pm, p1[r]);
;   { auto rr = __builtin_amdgcn_permlane32_swap(__float_as_uint(pm), __float_as_uint(pm), false, false);
;     pm = fmaxf(__uint_as_float(rr[0]), __uint_as_float(rr[1])); }
;   if (__builtin_expect(!force && __all(pm <= AT_THR * 1.4426950408889634f), 1)) { alpha = 1.f; }
;   else {
;     const float dlt = force ? pm : fmaxf(pm, 0.f);
;     alpha = force ? 1.f : __builtin_amdgcn_exp2f(-dlt); m_reg += dlt;
; #pragma unroll
;     for (int r = 0; r < 16; ++r) { p0[r] -= dlt; p1[r] -= dlt; }
;   }
; #pragma unroll
;   for (int r = 0; r < 16; ++r) p0[r] = __builtin_amdgcn_exp2f(p0[r]);
; }
; __device__ __forceinline__ void at_qkt(f32x16& p0, f32x16& p1, const char* Ks, const bf16x8* qr, int r32, int hi, float negm) {
; #pragma unroll
;   for (int r = 0; r < 16; ++r) { p0[r] = negm; p1[r] = negm; }
; #pragma unroll
;   for (int d0 = 0; d0 < 6; ++d0) {
;     const bf16x8 b0 = *(const bf16x8*)(Ks + r32 * AT_KROW + d0 * 32 + hi * 16);
;     const bf16x8 b1 = *(const bf16x8*)(Ks + (32 + r32) * AT_KROW + d0 * 32 + hi * 16);
;     p0 = MFMA(b0, qr[d0], p0);
;     p1 = MFMA(b1, qr[d0], p1);
;   }
; }
.Lat_rare1:
	ds_read_b128 v[184:187], v170 offset:26624
	ds_read_b128 v[188:191], v170 offset:33280
	s_waitcnt lgkmcnt(1)
	v_mfma_f32_32x32x16_bf16 v[32:47], v[184:187], v[80:83], 0
	s_waitcnt lgkmcnt(0)
	v_mfma_f32_32x32x16_bf16 v[48:63], v[188:191], v[80:83], 0
	s_nop 7
	s_nop 7
	ds_read_b128 v[184:187], v170 offset:26656
	ds_read_b128 v[188:191], v170 offset:33312
	s_waitcnt lgkmcnt(1)
	v_mfma_f32_32x32x16_bf16 v[32:47], v[184:187], v[84:87], v[32:47]
	s_waitcnt lgkmcnt(0)
	v_mfma_f32_32x32x16_bf16 v[48:63], v[188:191], v[84:87], v[48:63]
	s_nop 7
	s_nop 7
	ds_read_b128 v[184:187], v170 offset:26688
	ds_read_b128 v[188:191], v170 offset:33344
	s_waitcnt lgkmcnt(1)
	v_mfma_f32_32x32x16_bf16 v[32:47], v[184:187], v[88:91], v[32:47]
	s_waitcnt lgkmcnt(0)
	v_mfma_f32_32x32x16_bf16 v[48:63], v[188:191], v[88:91], v[48:63]
	s_nop 7
	s_nop 7
	ds_read_b128 v[184:187], v170 offset:26720
	ds_read_b128 v[188:191], v170 offset:33376
	s_waitcnt lgkmcnt(1)
	v_mfma_f32_32x32x16_bf16 v[32:47], v[184:187], v[92:95], v[32:47]
	s_waitcnt lgkmcnt(0)
	v_mfma_f32_32x32x16_bf16 v[48:63], v[188:191], v[92:95], v[48:63]
	s_nop 7
	s_nop 7
	ds_read_b128 v[184:187], v170 offset:26752
	ds_read_b128 v[188:191], v170 offset:33408
	s_waitcnt lgkmcnt(1)
	v_mfma_f32_32x32x16_bf16 v[32:47], v[184:187], v[96:99], v[32:47]
	s_waitcnt lgkmcnt(0)
	v_mfma_f32_32x32x16_bf16 v[48:63], v[188:191], v[96:99], v[48:63]
	s_nop 7
	s_nop 7
	ds_read_b128 v[184:187], v170 offset:26784
	ds_read_b128 v[188:191], v170 offset:33440
	s_waitcnt lgkmcnt(1)
	v_mfma_f32_32x32x16_bf16 v[32:47], v[184:187], v[100:103], v[32:47]
	s_waitcnt lgkmcnt(0)
	v_mfma_f32_32x32x16_bf16 v[48:63], v[188:191], v[100:103], v[48:63]
	s_nop 7
	s_nop 7
	s_nop 7
	s_nop 7
	v_max3_f32 v174, v32, v33, v34
	v_max3_f32 v175, v48, v49, v50
	v_max3_f32 v174, v174, v35, v36
	v_max3_f32 v175, v175, v51, v52
	v_max3_f32 v174, v174, v37, v38
	v_max3_f32 v175, v175, v53, v54
	v_max3_f32 v174, v174, v39, v40
	v_max3_f32 v175, v175, v55, v56
	v_max3_f32 v174, v174, v41, v42
	v_max3_f32 v175, v175, v57, v58
	v_max3_f32 v174, v174, v43, v44
	v_max3_f32 v175, v175, v59, v60
	v_max3_f32 v174, v174, v45, v46
	v_max3_f32 v175, v175, v61, v62
	v_max3_f32 v174, v174, v47, v63
	v_max_f32_e32 v174, v174, v175
	v_mov_b32_e32 v175, v174
	s_nop 1
	v_permlane32_swap_b32_e32 v174, v175
	v_max_f32_e32 v174, v174, v175
	v_sub_f32_e32 v174, v174, v172
	v_max_f32_e32 v174, 0, v174
	v_sub_f32_e32 v175, 0, v174
	v_exp_f32_e32 v181, v175
	v_add_f32_e32 v172, v172, v174
	v_sub_f32_e32 v32, v32, v172
	v_sub_f32_e32 v48, v48, v172
	v_sub_f32_e32 v33, v33, v172
	v_sub_f32_e32 v49, v49, v172
	v_sub_f32_e32 v34, v34, v172
	v_sub_f32_e32 v50, v50, v172
	v_sub_f32_e32 v35, v35, v172
	v_sub_f32_e32 v51, v51, v172
	v_sub_f32_e32 v36, v36, v172
	v_sub_f32_e32 v52, v52, v172
	v_sub_f32_e32 v37, v37, v172
	v_sub_f32_e32 v53, v53, v172
	v_sub_f32_e32 v38, v38, v172
	v_sub_f32_e32 v54, v54, v172
	v_sub_f32_e32 v39, v39, v172
	v_sub_f32_e32 v55, v55, v172
	v_sub_f32_e32 v40, v40, v172
	v_sub_f32_e32 v56, v56, v172
	v_sub_f32_e32 v41, v41, v172
	v_sub_f32_e32 v57, v57, v172
	v_sub_f32_e32 v42, v42, v172
	v_sub_f32_e32 v58, v58, v172
	v_sub_f32_e32 v43, v43, v172
	v_sub_f32_e32 v59, v59, v172
	v_sub_f32_e32 v44, v44, v172
	v_sub_f32_e32 v60, v60, v172
	v_sub_f32_e32 v45, v45, v172
	v_sub_f32_e32 v61, v61, v172
	v_sub_f32_e32 v46, v46, v172
	v_sub_f32_e32 v62, v62, v172
	v_sub_f32_e32 v47, v47, v172
	v_sub_f32_e32 v63, v63, v172
	v_sub_f32_e32 v64, 0, v172
	v_sub_f32_e32 v65, 0, v172
	v_sub_f32_e32 v66, 0, v172
	v_sub_f32_e32 v67, 0, v172
	v_sub_f32_e32 v68, 0, v172
	v_sub_f32_e32 v69, 0, v172
	v_sub_f32_e32 v70, 0, v172
	v_sub_f32_e32 v71, 0, v172
	v_sub_f32_e32 v72, 0, v172
	v_sub_f32_e32 v73, 0, v172
	v_sub_f32_e32 v74, 0, v172
	v_sub_f32_e32 v75, 0, v172
	v_sub_f32_e32 v76, 0, v172
	v_sub_f32_e32 v77, 0, v172
	v_sub_f32_e32 v78, 0, v172
	v_sub_f32_e32 v79, 0, v172
	v_mul_f32_e32 v173, v173, v181
	ds_write_b32 v244, v181
	s_waitcnt lgkmcnt(0)
	ds_read_b128 v[184:187], v245 offset:0
	ds_read_b128 v[188:191], v245 offset:32
	ds_read_b128 v[192:195], v245 offset:64
	ds_read_b128 v[196:199], v245 offset:96
	s_waitcnt lgkmcnt(0)
	v_mul_f32_e32 v0, v0, v184
	v_mul_f32_e32 v16, v16, v184
	v_mul_f32_e32 v1, v1, v185
	v_mul_f32_e32 v17, v17, v185
	v_mul_f32_e32 v2, v2, v186
	v_mul_f32_e32 v18, v18, v186
	v_mul_f32_e32 v3, v3, v187
	v_mul_f32_e32 v19, v19, v187
	v_mul_f32_e32 v4, v4, v188
	v_mul_f32_e32 v20, v20, v188
	v_mul_f32_e32 v5, v5, v189
	v_mul_f32_e32 v21, v21, v189
	v_mul_f32_e32 v6, v6, v190
	v_mul_f32_e32 v22, v22, v190
	v_mul_f32_e32 v7, v7, v191
	v_mul_f32_e32 v23, v23, v191
	v_mul_f32_e32 v8, v8, v192
	v_mul_f32_e32 v24, v24, v192
	v_mul_f32_e32 v9, v9, v193
	v_mul_f32_e32 v25, v25, v193
	v_mul_f32_e32 v10, v10, v194
	v_mul_f32_e32 v26, v26, v194
	v_mul_f32_e32 v11, v11, v195
	v_mul_f32_e32 v27, v27, v195
	v_mul_f32_e32 v12, v12, v196
	v_mul_f32_e32 v28, v28, v196
	v_mul_f32_e32 v13, v13, v197
	v_mul_f32_e32 v29, v29, v197
	v_mul_f32_e32 v14, v14, v198
	v_mul_f32_e32 v30, v30, v198
	v_mul_f32_e32 v15, v15, v199
	v_mul_f32_e32 v31, v31, v199
	v_exp_f32_e32 v32, v32
	v_exp_f32_e32 v48, v48
	v_exp_f32_e32 v33, v33
	v_exp_f32_e32 v49, v49
	v_exp_f32_e32 v34, v34
	v_exp_f32_e32 v50, v50
	v_exp_f32_e32 v35, v35
	v_exp_f32_e32 v51, v51
	v_exp_f32_e32 v36, v36
	v_exp_f32_e32 v52, v52
	v_exp_f32_e32 v37, v37
	v_exp_f32_e32 v53, v53
	v_exp_f32_e32 v38, v38
	v_exp_f32_e32 v54, v54
	v_exp_f32_e32 v39, v39
	v_exp_f32_e32 v55, v55
	v_exp_f32_e32 v40, v40
	v_exp_f32_e32 v56, v56
	v_exp_f32_e32 v41, v41
	v_exp_f32_e32 v57, v57
	v_exp_f32_e32 v42, v42
	v_exp_f32_e32 v58, v58
	v_exp_f32_e32 v43, v43
	v_exp_f32_e32 v59, v59
	v_exp_f32_e32 v44, v44
	v_exp_f32_e32 v60, v60
	v_exp_f32_e32 v45, v45
	v_exp_f32_e32 v61, v61
	v_exp_f32_e32 v46, v46
	v_exp_f32_e32 v62, v62
	v_exp_f32_e32 v47, v47
	v_exp_f32_e32 v63, v63
	v_add_f32_e32 v175, v32, v33
	v_add_f32_e32 v174, v48, v49
	v_add_f32_e32 v175, v175, v34
	v_add_f32_e32 v174, v174, v50
	v_add_f32_e32 v175, v175, v35
	v_add_f32_e32 v174, v174, v51
	v_add_f32_e32 v175, v175, v36
	v_add_f32_e32 v174, v174, v52
	v_add_f32_e32 v175, v175, v37
	v_add_f32_e32 v174, v174, v53
	v_add_f32_e32 v175, v175, v38
	v_add_f32_e32 v174, v174, v54
	v_add_f32_e32 v175, v175, v39
	v_add_f32_e32 v174, v174, v55
	v_add_f32_e32 v175, v175, v40
	v_add_f32_e32 v174, v174, v56
	v_add_f32_e32 v175, v175, v41
	v_add_f32_e32 v174, v174, v57
	v_add_f32_e32 v175, v175, v42
	v_add_f32_e32 v174, v174, v58
	v_add_f32_e32 v175, v175, v43
	v_add_f32_e32 v174, v174, v59
	v_add_f32_e32 v175, v175, v44
	v_add_f32_e32 v174, v174, v60
	v_add_f32_e32 v175, v175, v45
	v_add_f32_e32 v174, v174, v61
	v_add_f32_e32 v175, v175, v46
	v_add_f32_e32 v174, v174, v62
	v_add_f32_e32 v175, v175, v47
	v_add_f32_e32 v174, v174, v63
	v_add_f32_e32 v175, v175, v174
	s_branch .Lat_rare1_back
; #define MFMA(a, b, c) __builtin_amdgcn_mfma_f32_32x32x16_bf16((a), (b), (c), 0, 0, 0)
; __device__ __forceinline__ void at_partialSM(f32x16& p0, f32x16& p1, float& m_reg, float& alpha, bool force) {
;   float pm = p0[0];
; #pragma unroll
;   for (int r = 1; r < 16; ++r) pm = fmaxf(pm, p0[r]);
; #pragma unroll
;   for (int r = 0; r < 16; ++r) pm = fmaxf(pm, p1[r]);
;   { auto rr = __builtin_amdgcn_permlane32_swap(__float_as_uint(pm), __float_as_uint(pm), false, false);
;     pm = fmaxf(__uint_as_float(rr[0]), __uint_as_float(rr[1])); }
;   if (__builtin_expect(!force && __all(pm <= AT_THR * 1.4426950408889634f), 1)) { alpha = 1.f; }
;   else {
;     const float dlt = force ? pm : fmaxf(pm, 0.f);
;     alpha = force ? 1.f : __builtin_amdgcn_exp2f(-dlt); m_reg += dlt;
; #pragma unroll
;     for (int r = 0; r < 16; ++r) { p0[r] -= dlt; p1[r] -= dlt; }
;   }
; #pragma unroll
;   for (int r = 0; r < 16; ++r) p0[r] = __builtin_amdgcn_exp2f(p0[r]);
; }
; __device__ __forceinline__ void at_qkt(f32x16& p0, f32x16& p1, const char* Ks, const bf16x8* qr, int r32, int hi, float negm) {
; #pragma unroll
;   for (int r = 0; r < 16; ++r) { p0[r] = negm; p1[r] = negm; }
; #pragma unroll
;   for (int d0 = 0; d0 < 6; ++d0) {
;     const bf16x8 b0 = *(const bf16x8*)(Ks + r32 * AT_KROW + d0 * 32 + hi * 16);
;     const bf16x8 b1 = *(const bf16x8*)(Ks + (32 + r32) * AT_KROW + d0 * 32 + hi * 16);
;     p0 = MFMA(b0, qr[d0], p0);
;     p1 = MFMA(b1, qr[d0], p1);
;   }
; }
.Lat_rare2:
	ds_read_b128 v[184:187], v170 offset:39936
	ds_read_b128 v[188:191], v170 offset:46592
	s_waitcnt lgkmcnt(1)
	v_mfma_f32_32x32x16_bf16 v[32:47], v[184:187], v[80:83], 0
	s_waitcnt lgkmcnt(0)
	v_mfma_f32_32x32x16_bf16 v[48:63], v[188:191], v[80:83], 0
	s_nop 7
	s_nop 7
	ds_read_b128 v[184:187], v170 offset:39968
	ds_read_b128 v[188:191], v170 offset:46624
	s_waitcnt lgkmcnt(1)
	v_mfma_f32_32x32x16_bf16 v[32:47], v[184:187], v[84:87], v[32:47]
	s_waitcnt lgkmcnt(0)
	v_mfma_f32_32x32x16_bf16 v[48:63], v[188:191], v[84:87], v[48:63]
	s_nop 7
	s_nop 7
	ds_read_b128 v[184:187], v170 offset:40000
	ds_read_b128 v[188:191], v170 offset:46656
	s_waitcnt lgkmcnt(1)
	v_mfma_f32_32x32x16_bf16 v[32:47], v[184:187], v[88:91], v[32:47]
	s_waitcnt lgkmcnt(0)
	v_mfma_f32_32x32x16_bf16 v[48:63], v[188:191], v[88:91], v[48:63]
	s_nop 7
	s_nop 7
	ds_read_b128 v[184:187], v170 offset:40032
	ds_read_b128 v[188:191], v170 offset:46688
	s_waitcnt lgkmcnt(1)
	v_mfma_f32_32x32x16_bf16 v[32:47], v[184:187], v[92:95], v[32:47]
	s_waitcnt lgkmcnt(0)
	v_mfma_f32_32x32x16_bf16 v[48:63], v[188:191], v[92:95], v[48:63]
	s_nop 7
	s_nop 7
	ds_read_b128 v[184:187], v170 offset:40064
	ds_read_b128 v[188:191], v170 offset:46720
	s_waitcnt lgkmcnt(1)
	v_mfma_f32_32x32x16_bf16 v[32:47], v[184:187], v[96:99], v[32:47]
	s_waitcnt lgkmcnt(0)
	v_mfma_f32_32x32x16_bf16 v[48:63], v[188:191], v[96:99], v[48:63]
	s_nop 7
	s_nop 7
	ds_read_b128 v[184:187], v170 offset:40096
	ds_read_b128 v[188:191], v170 offset:46752
	s_waitcnt lgkmcnt(1)
	v_mfma_f32_32x32x16_bf16 v[32:47], v[184:187], v[100:103], v[32:47]
	s_waitcnt lgkmcnt(0)
	v_mfma_f32_32x32x16_bf16 v[48:63], v[188:191], v[100:103], v[48:63]
	s_nop 7
	s_nop 7
	s_nop 7
	s_nop 7
	v_max3_f32 v174, v32, v33, v34
	v_max3_f32 v175, v48, v49, v50
	v_max3_f32 v174, v174, v35, v36
	v_max3_f32 v175, v175, v51, v52
	v_max3_f32 v174, v174, v37, v38
	v_max3_f32 v175, v175, v53, v54
	v_max3_f32 v174, v174, v39, v40
	v_max3_f32 v175, v175, v55, v56
	v_max3_f32 v174, v174, v41, v42
	v_max3_f32 v175, v175, v57, v58
	v_max3_f32 v174, v174, v43, v44
	v_max3_f32 v175, v175, v59, v60
	v_max3_f32 v174, v174, v45, v46
	v_max3_f32 v175, v175, v61, v62
	v_max3_f32 v174, v174, v47, v63
	v_max_f32_e32 v174, v174, v175
	v_mov_b32_e32 v175, v174
	s_nop 1
	v_permlane32_swap_b32_e32 v174, v175
	v_max_f32_e32 v174, v174, v175
	v_sub_f32_e32 v174, v174, v172
	v_max_f32_e32 v174, 0, v174
	v_sub_f32_e32 v175, 0, v174
	v_exp_f32_e32 v181, v175
	v_add_f32_e32 v172, v172, v174
	v_sub_f32_e32 v32, v32, v172
	v_sub_f32_e32 v48, v48, v172
	v_sub_f32_e32 v33, v33, v172
	v_sub_f32_e32 v49, v49, v172
	v_sub_f32_e32 v34, v34, v172
	v_sub_f32_e32 v50, v50, v172
	v_sub_f32_e32 v35, v35, v172
	v_sub_f32_e32 v51, v51, v172
	v_sub_f32_e32 v36, v36, v172
	v_sub_f32_e32 v52, v52, v172
	v_sub_f32_e32 v37, v37, v172
	v_sub_f32_e32 v53, v53, v172
	v_sub_f32_e32 v38, v38, v172
	v_sub_f32_e32 v54, v54, v172
	v_sub_f32_e32 v39, v39, v172
	v_sub_f32_e32 v55, v55, v172
	v_sub_f32_e32 v40, v40, v172
	v_sub_f32_e32 v56, v56, v172
	v_sub_f32_e32 v41, v41, v172
	v_sub_f32_e32 v57, v57, v172
	v_sub_f32_e32 v42, v42, v172
	v_sub_f32_e32 v58, v58, v172
	v_sub_f32_e32 v43, v43, v172
	v_sub_f32_e32 v59, v59, v172
	v_sub_f32_e32 v44, v44, v172
	v_sub_f32_e32 v60, v60, v172
	v_sub_f32_e32 v45, v45, v172
	v_sub_f32_e32 v61, v61, v172
	v_sub_f32_e32 v46, v46, v172
	v_sub_f32_e32 v62, v62, v172
	v_sub_f32_e32 v47, v47, v172
	v_sub_f32_e32 v63, v63, v172
	v_sub_f32_e32 v64, 0, v172
	v_sub_f32_e32 v65, 0, v172
	v_sub_f32_e32 v66, 0, v172
	v_sub_f32_e32 v67, 0, v172
	v_sub_f32_e32 v68, 0, v172
	v_sub_f32_e32 v69, 0, v172
	v_sub_f32_e32 v70, 0, v172
	v_sub_f32_e32 v71, 0, v172
	v_sub_f32_e32 v72, 0, v172
	v_sub_f32_e32 v73, 0, v172
	v_sub_f32_e32 v74, 0, v172
	v_sub_f32_e32 v75, 0, v172
	v_sub_f32_e32 v76, 0, v172
	v_sub_f32_e32 v77, 0, v172
	v_sub_f32_e32 v78, 0, v172
	v_sub_f32_e32 v79, 0, v172
	v_mul_f32_e32 v173, v173, v181
	ds_write_b32 v244, v181
	s_waitcnt lgkmcnt(0)
	ds_read_b128 v[184:187], v245 offset:0
	ds_read_b128 v[188:191], v245 offset:32
	ds_read_b128 v[192:195], v245 offset:64
	ds_read_b128 v[196:199], v245 offset:96
	s_waitcnt lgkmcnt(0)
	v_mul_f32_e32 v0, v0, v184
	v_mul_f32_e32 v16, v16, v184
	v_mul_f32_e32 v1, v1, v185
	v_mul_f32_e32 v17, v17, v185
	v_mul_f32_e32 v2, v2, v186
	v_mul_f32_e32 v18, v18, v186
	v_mul_f32_e32 v3, v3, v187
	v_mul_f32_e32 v19, v19, v187
	v_mul_f32_e32 v4, v4, v188
	v_mul_f32_e32 v20, v20, v188
	v_mul_f32_e32 v5, v5, v189
	v_mul_f32_e32 v21, v21, v189
	v_mul_f32_e32 v6, v6, v190
	v_mul_f32_e32 v22, v22, v190
	v_mul_f32_e32 v7, v7, v191
	v_mul_f32_e32 v23, v23, v191
	v_mul_f32_e32 v8, v8, v192
	v_mul_f32_e32 v24, v24, v192
	v_mul_f32_e32 v9, v9, v193
	v_mul_f32_e32 v25, v25, v193
	v_mul_f32_e32 v10, v10, v194
	v_mul_f32_e32 v26, v26, v194
	v_mul_f32_e32 v11, v11, v195
	v_mul_f32_e32 v27, v27, v195
	v_mul_f32_e32 v12, v12, v196
	v_mul_f32_e32 v28, v28, v196
	v_mul_f32_e32 v13, v13, v197
	v_mul_f32_e32 v29, v29, v197
	v_mul_f32_e32 v14, v14, v198
	v_mul_f32_e32 v30, v30, v198
	v_mul_f32_e32 v15, v15, v199
	v_mul_f32_e32 v31, v31, v199
	v_exp_f32_e32 v32, v32
	v_exp_f32_e32 v48, v48
	v_exp_f32_e32 v33, v33
	v_exp_f32_e32 v49, v49
	v_exp_f32_e32 v34, v34
	v_exp_f32_e32 v50, v50
	v_exp_f32_e32 v35, v35
	v_exp_f32_e32 v51, v51
	v_exp_f32_e32 v36, v36
	v_exp_f32_e32 v52, v52
	v_exp_f32_e32 v37, v37
	v_exp_f32_e32 v53, v53
	v_exp_f32_e32 v38, v38
	v_exp_f32_e32 v54, v54
	v_exp_f32_e32 v39, v39
	v_exp_f32_e32 v55, v55
	v_exp_f32_e32 v40, v40
	v_exp_f32_e32 v56, v56
	v_exp_f32_e32 v41, v41
	v_exp_f32_e32 v57, v57
	v_exp_f32_e32 v42, v42
	v_exp_f32_e32 v58, v58
	v_exp_f32_e32 v43, v43
	v_exp_f32_e32 v59, v59
	v_exp_f32_e32 v44, v44
	v_exp_f32_e32 v60, v60
	v_exp_f32_e32 v45, v45
	v_exp_f32_e32 v61, v61
	v_exp_f32_e32 v46, v46
	v_exp_f32_e32 v62, v62
	v_exp_f32_e32 v47, v47
	v_exp_f32_e32 v63, v63
	v_add_f32_e32 v175, v32, v33
	v_add_f32_e32 v174, v48, v49
	v_add_f32_e32 v175, v175, v34
	v_add_f32_e32 v174, v174, v50
	v_add_f32_e32 v175, v175, v35
	v_add_f32_e32 v174, v174, v51
	v_add_f32_e32 v175, v175, v36
	v_add_f32_e32 v174, v174, v52
	v_add_f32_e32 v175, v175, v37
	v_add_f32_e32 v174, v174, v53
	v_add_f32_e32 v175, v175, v38
	v_add_f32_e32 v174, v174, v54
	v_add_f32_e32 v175, v175, v39
	v_add_f32_e32 v174, v174, v55
	v_add_f32_e32 v175, v175, v40
	v_add_f32_e32 v174, v174, v56
	v_add_f32_e32 v175, v175, v41
	v_add_f32_e32 v174, v174, v57
	v_add_f32_e32 v175, v175, v42
	v_add_f32_e32 v174, v174, v58
	v_add_f32_e32 v175, v175, v43
	v_add_f32_e32 v174, v174, v59
	v_add_f32_e32 v175, v175, v44
	v_add_f32_e32 v174, v174, v60
	v_add_f32_e32 v175, v175, v45
	v_add_f32_e32 v174, v174, v61
	v_add_f32_e32 v175, v175, v46
	v_add_f32_e32 v174, v174, v62
	v_add_f32_e32 v175, v175, v47
	v_add_f32_e32 v174, v174, v63
	v_add_f32_e32 v175, v175, v174
	s_branch .Lat_rare2_back
; #define MFMA(a, b, c) __builtin_amdgcn_mfma_f32_32x32x16_bf16((a), (b), (c), 0, 0, 0)
; __device__ __forceinline__ void at_partialSM(f32x16& p0, f32x16& p1, float& m_reg, float& alpha, bool force) {
;   float pm = p0[0];
; #pragma unroll
;   for (int r = 1; r < 16; ++r) pm = fmaxf(pm, p0[r]);
; #pragma unroll
;   for (int r = 0; r < 16; ++r) pm = fmaxf(pm, p1[r]);
;   { auto rr = __builtin_amdgcn_permlane32_swap(__float_as_uint(pm), __float_as_uint(pm), false, false);
;     pm = fmaxf(__uint_as_float(rr[0]), __uint_as_float(rr[1])); }
;   if (__builtin_expect(!force && __all(pm <= AT_THR * 1.4426950408889634f), 1)) { alpha = 1.f; }
;   else {
;     const float dlt = force ? pm : fmaxf(pm, 0.f);
;     alpha = force ? 1.f : __builtin_amdgcn_exp2f(-dlt); m_reg += dlt;
; #pragma unroll
;     for (int r = 0; r < 16; ++r) { p0[r] -= dlt; p1[r] -= dlt; }
;   }
; #pragma unroll
;   for (int r = 0; r < 16; ++r) p0[r] = __builtin_amdgcn_exp2f(p0[r]);
; }
; __device__ __forceinline__ void at_qkt(f32x16& p0, f32x16& p1, const char* Ks, const bf16x8* qr, int r32, int hi, float negm) {
; #pragma unroll
;   for (int r = 0; r < 16; ++r) { p0[r] = negm; p1[r] = negm; }
; #pragma unroll
;   for (int d0 = 0; d0 < 6; ++d0) {
;     const bf16x8 b0 = *(const bf16x8*)(Ks + r32 * AT_KROW + d0 * 32 + hi * 16);
;     const bf16x8 b1 = *(const bf16x8*)(Ks + (32 + r32) * AT_KROW + d0 * 32 + hi * 16);
;     p0 = MFMA(b0, qr[d0], p0);
;     p1 = MFMA(b1, qr[d0], p1);
;   }
; }
.Lat_rare3:
	ds_read_b128 v[184:187], v170 offset:0
	ds_read_b128 v[188:191], v170 offset:6656
	s_waitcnt lgkmcnt(1)
	v_mfma_f32_32x32x16_bf16 v[32:47], v[184:187], v[80:83], 0
	s_waitcnt lgkmcnt(0)
	v_mfma_f32_32x32x16_bf16 v[48:63], v[188:191], v[80:83], 0
	s_nop 7
	s_nop 7
	ds_read_b128 v[184:187], v170 offset:32
	ds_read_b128 v[188:191], v170 offset:6688
	s_waitcnt lgkmcnt(1)
	v_mfma_f32_32x32x16_bf16 v[32:47], v[184:187], v[84:87], v[32:47]
	s_waitcnt lgkmcnt(0)
	v_mfma_f32_32x32x16_bf16 v[48:63], v[188:191], v[84:87], v[48:63]
	s_nop 7
	s_nop 7
	ds_read_b128 v[184:187], v170 offset:64
	ds_read_b128 v[188:191], v170 offset:6720
	s_waitcnt lgkmcnt(1)
	v_mfma_f32_32x32x16_bf16 v[32:47], v[184:187], v[88:91], v[32:47]
	s_waitcnt lgkmcnt(0)
	v_mfma_f32_32x32x16_bf16 v[48:63], v[188:191], v[88:91], v[48:63]
	s_nop 7
	s_nop 7
	ds_read_b128 v[184:187], v170 offset:96
	ds_read_b128 v[188:191], v170 offset:6752
	s_waitcnt lgkmcnt(1)
	v_mfma_f32_32x32x16_bf16 v[32:47], v[184:187], v[92:95], v[32:47]
	s_waitcnt lgkmcnt(0)
	v_mfma_f32_32x32x16_bf16 v[48:63], v[188:191], v[92:95], v[48:63]
	s_nop 7
	s_nop 7
	ds_read_b128 v[184:187], v170 offset:128
	ds_read_b128 v[188:191], v170 offset:6784
	s_waitcnt lgkmcnt(1)
	v_mfma_f32_32x32x16_bf16 v[32:47], v[184:187], v[96:99], v[32:47]
	s_waitcnt lgkmcnt(0)
	v_mfma_f32_32x32x16_bf16 v[48:63], v[188:191], v[96:99], v[48:63]
	s_nop 7
	s_nop 7
	ds_read_b128 v[184:187], v170 offset:160
	ds_read_b128 v[188:191], v170 offset:6816
	s_waitcnt lgkmcnt(1)
	v_mfma_f32_32x32x16_bf16 v[32:47], v[184:187], v[100:103], v[32:47]
	s_waitcnt lgkmcnt(0)
	v_mfma_f32_32x32x16_bf16 v[48:63], v[188:191], v[100:103], v[48:63]
	s_nop 7
	s_nop 7
	s_nop 7
	s_nop 7
	v_max3_f32 v174, v32, v33, v34
	v_max3_f32 v175, v48, v49, v50
	v_max3_f32 v174, v174, v35, v36
	v_max3_f32 v175, v175, v51, v52
	v_max3_f32 v174, v174, v37, v38
	v_max3_f32 v175, v175, v53, v54
	v_max3_f32 v174, v174, v39, v40
	v_max3_f32 v175, v175, v55, v56
	v_max3_f32 v174, v174, v41, v42
	v_max3_f32 v175, v175, v57, v58
	v_max3_f32 v174, v174, v43, v44
	v_max3_f32 v175, v175, v59, v60
	v_max3_f32 v174, v174, v45, v46
	v_max3_f32 v175, v175, v61, v62
	v_max3_f32 v174, v174, v47, v63
	v_max_f32_e32 v174, v174, v175
	v_mov_b32_e32 v175, v174
	s_nop 1
	v_permlane32_swap_b32_e32 v174, v175
	v_max_f32_e32 v174, v174, v175
	v_sub_f32_e32 v174, v174, v172
	v_max_f32_e32 v174, 0, v174
	v_sub_f32_e32 v175, 0, v174
	v_exp_f32_e32 v181, v175
	v_add_f32_e32 v172, v172, v174
	v_sub_f32_e32 v32, v32, v172
	v_sub_f32_e32 v48, v48, v172
	v_sub_f32_e32 v33, v33, v172
	v_sub_f32_e32 v49, v49, v172
	v_sub_f32_e32 v34, v34, v172
	v_sub_f32_e32 v50, v50, v172
	v_sub_f32_e32 v35, v35, v172
	v_sub_f32_e32 v51, v51, v172
	v_sub_f32_e32 v36, v36, v172
	v_sub_f32_e32 v52, v52, v172
	v_sub_f32_e32 v37, v37, v172
	v_sub_f32_e32 v53, v53, v172
	v_sub_f32_e32 v38, v38, v172
	v_sub_f32_e32 v54, v54, v172
	v_sub_f32_e32 v39, v39, v172
	v_sub_f32_e32 v55, v55, v172
	v_sub_f32_e32 v40, v40, v172
	v_sub_f32_e32 v56, v56, v172
	v_sub_f32_e32 v41, v41, v172
	v_sub_f32_e32 v57, v57, v172
	v_sub_f32_e32 v42, v42, v172
	v_sub_f32_e32 v58, v58, v172
	v_sub_f32_e32 v43, v43, v172
	v_sub_f32_e32 v59, v59, v172
	v_sub_f32_e32 v44, v44, v172
	v_sub_f32_e32 v60, v60, v172
	v_sub_f32_e32 v45, v45, v172
	v_sub_f32_e32 v61, v61, v172
	v_sub_f32_e32 v46, v46, v172
	v_sub_f32_e32 v62, v62, v172
	v_sub_f32_e32 v47, v47, v172
	v_sub_f32_e32 v63, v63, v172
	v_sub_f32_e32 v64, 0, v172
	v_sub_f32_e32 v65, 0, v172
	v_sub_f32_e32 v66, 0, v172
	v_sub_f32_e32 v67, 0, v172
	v_sub_f32_e32 v68, 0, v172
	v_sub_f32_e32 v69, 0, v172
	v_sub_f32_e32 v70, 0, v172
	v_sub_f32_e32 v71, 0, v172
	v_sub_f32_e32 v72, 0, v172
	v_sub_f32_e32 v73, 0, v172
	v_sub_f32_e32 v74, 0, v172
	v_sub_f32_e32 v75, 0, v172
	v_sub_f32_e32 v76, 0, v172
	v_sub_f32_e32 v77, 0, v172
	v_sub_f32_e32 v78, 0, v172
	v_sub_f32_e32 v79, 0, v172
	v_mul_f32_e32 v173, v173, v181
	ds_write_b32 v244, v181
	s_waitcnt lgkmcnt(0)
	ds_read_b128 v[184:187], v245 offset:0
	ds_read_b128 v[188:191], v245 offset:32
	ds_read_b128 v[192:195], v245 offset:64
	ds_read_b128 v[196:199], v245 offset:96
	s_waitcnt lgkmcnt(0)
	v_mul_f32_e32 v0, v0, v184
	v_mul_f32_e32 v16, v16, v184
	v_mul_f32_e32 v1, v1, v185
	v_mul_f32_e32 v17, v17, v185
	v_mul_f32_e32 v2, v2, v186
	v_mul_f32_e32 v18, v18, v186
	v_mul_f32_e32 v3, v3, v187
	v_mul_f32_e32 v19, v19, v187
	v_mul_f32_e32 v4, v4, v188
	v_mul_f32_e32 v20, v20, v188
	v_mul_f32_e32 v5, v5, v189
	v_mul_f32_e32 v21, v21, v189
	v_mul_f32_e32 v6, v6, v190
	v_mul_f32_e32 v22, v22, v190
	v_mul_f32_e32 v7, v7, v191
	v_mul_f32_e32 v23, v23, v191
	v_mul_f32_e32 v8, v8, v192
	v_mul_f32_e32 v24, v24, v192
	v_mul_f32_e32 v9, v9, v193
	v_mul_f32_e32 v25, v25, v193
	v_mul_f32_e32 v10, v10, v194
	v_mul_f32_e32 v26, v26, v194
	v_mul_f32_e32 v11, v11, v195
	v_mul_f32_e32 v27, v27, v195
	v_mul_f32_e32 v12, v12, v196
	v_mul_f32_e32 v28, v28, v196
	v_mul_f32_e32 v13, v13, v197
	v_mul_f32_e32 v29, v29, v197
	v_mul_f32_e32 v14, v14, v198
	v_mul_f32_e32 v30, v30, v198
	v_mul_f32_e32 v15, v15, v199
	v_mul_f32_e32 v31, v31, v199
	v_exp_f32_e32 v32, v32
	v_exp_f32_e32 v48, v48
	v_exp_f32_e32 v33, v33
	v_exp_f32_e32 v49, v49
	v_exp_f32_e32 v34, v34
	v_exp_f32_e32 v50, v50
	v_exp_f32_e32 v35, v35
	v_exp_f32_e32 v51, v51
	v_exp_f32_e32 v36, v36
	v_exp_f32_e32 v52, v52
	v_exp_f32_e32 v37, v37
	v_exp_f32_e32 v53, v53
	v_exp_f32_e32 v38, v38
	v_exp_f32_e32 v54, v54
	v_exp_f32_e32 v39, v39
	v_exp_f32_e32 v55, v55
	v_exp_f32_e32 v40, v40
	v_exp_f32_e32 v56, v56
	v_exp_f32_e32 v41, v41
	v_exp_f32_e32 v57, v57
	v_exp_f32_e32 v42, v42
	v_exp_f32_e32 v58, v58
	v_exp_f32_e32 v43, v43
	v_exp_f32_e32 v59, v59
	v_exp_f32_e32 v44, v44
	v_exp_f32_e32 v60, v60
	v_exp_f32_e32 v45, v45
	v_exp_f32_e32 v61, v61
	v_exp_f32_e32 v46, v46
	v_exp_f32_e32 v62, v62
	v_exp_f32_e32 v47, v47
	v_exp_f32_e32 v63, v63
	v_add_f32_e32 v175, v32, v33
	v_add_f32_e32 v174, v48, v49
	v_add_f32_e32 v175, v175, v34
	v_add_f32_e32 v174, v174, v50
	v_add_f32_e32 v175, v175, v35
	v_add_f32_e32 v174, v174, v51
	v_add_f32_e32 v175, v175, v36
	v_add_f32_e32 v174, v174, v52
	v_add_f32_e32 v175, v175, v37
	v_add_f32_e32 v174, v174, v53
	v_add_f32_e32 v175, v175, v38
	v_add_f32_e32 v174, v174, v54
	v_add_f32_e32 v175, v175, v39
	v_add_f32_e32 v174, v174, v55
	v_add_f32_e32 v175, v175, v40
	v_add_f32_e32 v174, v174, v56
	v_add_f32_e32 v175, v175, v41
	v_add_f32_e32 v174, v174, v57
	v_add_f32_e32 v175, v175, v42
	v_add_f32_e32 v174, v174, v58
	v_add_f32_e32 v175, v175, v43
	v_add_f32_e32 v174, v174, v59
	v_add_f32_e32 v175, v175, v44
	v_add_f32_e32 v174, v174, v60
	v_add_f32_e32 v175, v175, v45
	v_add_f32_e32 v174, v174, v61
	v_add_f32_e32 v175, v175, v46
	v_add_f32_e32 v174, v174, v62
	v_add_f32_e32 v175, v175, v47
	v_add_f32_e32 v174, v174, v63
	v_add_f32_e32 v175, v175, v174
	s_branch .Lat_rare3_back
